# in-proj epilogue RoPE rows: next row-group's rope-table loads prefetched one group ahead (ping-pong regs), partner bias loaded once per pass, counted vmcnt
# speedup vs baseline: 1.0011x; 1.0011x over previous
; #define RAW_BARRIER() do { asm volatile("s_waitcnt lgkmcnt(0)" ::: "memory"); __builtin_amdgcn_s_barrier(); } while (0)
; #define GEMM_READ4(A_, B_, FA, FB) asm volatile( \
;         "ds_read_b128 %0, %6\n\tds_read_b128 %1, %6 offset:2048\n\tds_read_b128 %2, %6 offset:4096\n\tds_read_b128 %3, %6 offset:6144\n\t" \
;         "ds_read_b128 %4, %7\n\tds_read_b128 %5, %7 offset:2048" \
;         : "=&v"(FA[0]), "=&v"(FA[1]), "=&v"(FA[2]), "=&v"(FA[3]), "=&v"(FB[0]), "=&v"(FB[1]) : "v"(A_), "v"(B_) : "memory")
; #define GEMM_READ2(A_, B_, FA, FB) asm volatile( \
;         "ds_read_b128 %0, %4\n\tds_read_b128 %1, %4 offset:2048\n\tds_read_b128 %2, %5\n\tds_read_b128 %3, %5 offset:2048" \
;         : "=&v"(FA[0]), "=&v"(FA[1]), "=&v"(FB[0]), "=&v"(FB[1]) : "v"(A_), "v"(B_) : "memory")
; #define GEMM_WAIT4(FA, FB) asm volatile("s_waitcnt lgkmcnt(0)" : "+v"(FA[0]), "+v"(FA[1]), "+v"(FA[2]), "+v"(FA[3]), "+v"(FB[0]), "+v"(FB[1]) :: "memory")
; #define GEMM_WAIT2(FA, FB) asm volatile("s_waitcnt lgkmcnt(0)" : "+v"(FA[0]), "+v"(FA[1]), "+v"(FB[0]), "+v"(FB[1]) :: "memory")
; template <int WM, class Epi>
; DI void gemm_mfma(const bf16_t* __restrict__ A, const bf16_t* __restrict__ Bt, int Arows, int Brows, int MT, int NT, unsigned char* smem, int bid, int nb, int wave, Epi epi) {
;     ...
; #pragma unroll 1
;     for (int kt = 0; kt < NKT; ++kt) {
;       const int ahead = (NKT - 1 - kt < NST - 2) ? (NKT - 1 - kt) : (NST - 2);
;       if (NI == 4) { if (ahead == 2) asm volatile("s_waitcnt vmcnt(8)" ::: "memory"); else if (ahead == 1) asm volatile("s_waitcnt vmcnt(4)" ::: "memory"); else asm volatile("s_waitcnt vmcnt(0)" ::: "memory"); }
;       else { if (ahead == 1) asm volatile("s_waitcnt vmcnt(6)" ::: "memory"); else asm volatile("s_waitcnt vmcnt(0)" ::: "memory"); }
;       RAW_BARRIER();
;       if (kt + NST - 1 < NKT) issue(kt + NST - 1, (kt + NST - 1) % NST);
;       const unsigned sb = lds0 + (unsigned)((kt % NST) * STAGE);
;       const unsigned a0 = sb + offA0, a1 = sb + offA1, b0 = sb + offB0, b1 = sb + offB1;
;       if constexpr (WM == 4) GEMM_READ4(a0, b0, fa0, fb0); else GEMM_READ2(a0, b0, fa0, fb0);
;       GEMM_MMA(fa1, fb1);
;       if constexpr (WM == 4) { GEMM_WAIT4(fa0, fb0); GEMM_READ4(a1, b1, fa1, fb1); } else { GEMM_WAIT2(fa0, fb0); GEMM_READ2(a1, b1, fa1, fb1); }
;       GEMM_MMA(fa0, fb0);
;     }
.Lg16_tail:
	s_setprio 1
	v_mfma_f32_16x16x32_bf16 v[0:3], v[128:131], v[144:147], v[0:3]
	s_mul_i32 s26, s6, 0xab
	s_bfe_u32 s26, s26, 0x70009
	s_mul_i32 s26, s26, 3
	s_sub_i32 s6, s6, s26
	s_and_b32 s6, s6, 0xff
	s_mulk_i32 s6, 0x6000
	v_add_u32_e32 v160, s6, v159
	v_add_u32_e32 v170, s6, v165
	ds_read_b128 v[196:199], v160
	ds_read_b128 v[200:203], v160 offset:1024
	v_mfma_f32_16x16x32_bf16 v[4:7], v[128:131], v[148:151], v[4:7]
	ds_read_b128 v[204:207], v160 offset:2048
	ds_read_b128 v[208:211], v160 offset:3072
	v_mfma_f32_16x16x32_bf16 v[8:11], v[128:131], v[228:231], v[8:11]
	ds_read_b128 v[212:215], v170
	ds_read_b128 v[216:219], v170 offset:1024
	v_mfma_f32_16x16x32_bf16 v[12:15], v[128:131], v[232:235], v[12:15]
	ds_read_b128 v[220:223], v170 offset:2048
	ds_read_b128 v[224:227], v170 offset:3072
	v_mfma_f32_16x16x32_bf16 v[16:19], v[132:135], v[144:147], v[16:19]
	v_mfma_f32_16x16x32_bf16 v[20:23], v[132:135], v[148:151], v[20:23]
	v_mfma_f32_16x16x32_bf16 v[24:27], v[132:135], v[228:231], v[24:27]
	v_mfma_f32_16x16x32_bf16 v[28:31], v[132:135], v[232:235], v[28:31]
	v_mfma_f32_16x16x32_bf16 v[32:35], v[136:139], v[144:147], v[32:35]
	v_mfma_f32_16x16x32_bf16 v[36:39], v[136:139], v[148:151], v[36:39]
	v_mfma_f32_16x16x32_bf16 v[40:43], v[136:139], v[228:231], v[40:43]
	v_mfma_f32_16x16x32_bf16 v[44:47], v[136:139], v[232:235], v[44:47]
	v_mfma_f32_16x16x32_bf16 v[48:51], v[140:143], v[144:147], v[48:51]
	v_mfma_f32_16x16x32_bf16 v[52:55], v[140:143], v[148:151], v[52:55]
	v_mfma_f32_16x16x32_bf16 v[56:59], v[140:143], v[228:231], v[56:59]
	v_mfma_f32_16x16x32_bf16 v[60:63], v[140:143], v[232:235], v[60:63]
	s_setprio 0
	s_waitcnt lgkmcnt(0)
	ds_read_b128 v[128:131], v160 offset:4096
	ds_read_b128 v[132:135], v160 offset:5120
	ds_read_b128 v[136:139], v160 offset:6144
	ds_read_b128 v[140:143], v160 offset:7168
	s_setprio 1
	v_mfma_f32_16x16x32_bf16 v[64:67], v[196:199], v[212:215], v[64:67]
	v_mfma_f32_16x16x32_bf16 v[68:71], v[196:199], v[216:219], v[68:71]
	v_mfma_f32_16x16x32_bf16 v[72:75], v[196:199], v[220:223], v[72:75]
	v_mfma_f32_16x16x32_bf16 v[76:79], v[196:199], v[224:227], v[76:79]
	v_mfma_f32_16x16x32_bf16 v[80:83], v[200:203], v[212:215], v[80:83]
	v_mfma_f32_16x16x32_bf16 v[84:87], v[200:203], v[216:219], v[84:87]
	v_mfma_f32_16x16x32_bf16 v[88:91], v[200:203], v[220:223], v[88:91]
	v_mfma_f32_16x16x32_bf16 v[92:95], v[200:203], v[224:227], v[92:95]
	v_mfma_f32_16x16x32_bf16 v[96:99], v[204:207], v[212:215], v[96:99]
	v_mfma_f32_16x16x32_bf16 v[100:103], v[204:207], v[216:219], v[100:103]
	v_mfma_f32_16x16x32_bf16 v[104:107], v[204:207], v[220:223], v[104:107]
	v_mfma_f32_16x16x32_bf16 v[108:111], v[204:207], v[224:227], v[108:111]
	v_mfma_f32_16x16x32_bf16 v[112:115], v[208:211], v[212:215], v[112:115]
	v_mfma_f32_16x16x32_bf16 v[116:119], v[208:211], v[216:219], v[116:119]
	v_mfma_f32_16x16x32_bf16 v[120:123], v[208:211], v[220:223], v[120:123]
	v_mfma_f32_16x16x32_bf16 v[124:127], v[208:211], v[224:227], v[124:127]
	s_setprio 0
	s_add_u32 s0, s0, 0x46000
	s_addc_u32 s1, s1, 0
	s_add_u32 s4, s4, 0x120000
	s_addc_u32 s5, s5, 0
	s_add_i32 s21, s21, 1
	s_waitcnt vmcnt(0)
	s_waitcnt lgkmcnt(0)
	s_add_i32 s6, s21, -2
	s_barrier
	s_setprio 1
	v_mfma_f32_16x16x32_bf16 v[0:3], v[128:131], v[212:215], v[0:3]
	s_mul_i32 s26, s6, 0xab
	s_bfe_u32 s26, s26, 0x70009
	s_mul_i32 s26, s26, 3
	s_sub_i32 s6, s6, s26
	s_and_b32 s6, s6, 0xff
	s_mulk_i32 s6, 0x6000
	v_add_u32_e32 v160, s6, v159
	v_add_u32_e32 v170, s6, v165
	ds_read_b128 v[196:199], v160
	ds_read_b128 v[200:203], v160 offset:1024
	v_mfma_f32_16x16x32_bf16 v[4:7], v[128:131], v[216:219], v[4:7]
	ds_read_b128 v[204:207], v160 offset:2048
	ds_read_b128 v[208:211], v160 offset:3072
	v_mfma_f32_16x16x32_bf16 v[8:11], v[128:131], v[220:223], v[8:11]
	ds_read_b128 v[144:147], v170
	ds_read_b128 v[148:151], v170 offset:1024
	v_mfma_f32_16x16x32_bf16 v[12:15], v[128:131], v[224:227], v[12:15]
	ds_read_b128 v[228:231], v170 offset:2048
	ds_read_b128 v[232:235], v170 offset:3072
	v_mfma_f32_16x16x32_bf16 v[16:19], v[132:135], v[212:215], v[16:19]
	v_mfma_f32_16x16x32_bf16 v[20:23], v[132:135], v[216:219], v[20:23]
	v_mfma_f32_16x16x32_bf16 v[24:27], v[132:135], v[220:223], v[24:27]
	v_mfma_f32_16x16x32_bf16 v[28:31], v[132:135], v[224:227], v[28:31]
	v_mfma_f32_16x16x32_bf16 v[32:35], v[136:139], v[212:215], v[32:35]
	v_mfma_f32_16x16x32_bf16 v[36:39], v[136:139], v[216:219], v[36:39]
	v_mfma_f32_16x16x32_bf16 v[40:43], v[136:139], v[220:223], v[40:43]
	v_mfma_f32_16x16x32_bf16 v[44:47], v[136:139], v[224:227], v[44:47]
	v_mfma_f32_16x16x32_bf16 v[48:51], v[140:143], v[212:215], v[48:51]
	v_mfma_f32_16x16x32_bf16 v[52:55], v[140:143], v[216:219], v[52:55]
	v_mfma_f32_16x16x32_bf16 v[56:59], v[140:143], v[220:223], v[56:59]
	v_mfma_f32_16x16x32_bf16 v[60:63], v[140:143], v[224:227], v[60:63]
	s_setprio 0
	s_waitcnt lgkmcnt(0)
	ds_read_b128 v[128:131], v160 offset:4096
	ds_read_b128 v[132:135], v160 offset:5120
	ds_read_b128 v[136:139], v160 offset:6144
	ds_read_b128 v[140:143], v160 offset:7168
	s_setprio 1
	v_mfma_f32_16x16x32_bf16 v[64:67], v[196:199], v[144:147], v[64:67]
	v_mfma_f32_16x16x32_bf16 v[68:71], v[196:199], v[148:151], v[68:71]
	v_mfma_f32_16x16x32_bf16 v[72:75], v[196:199], v[228:231], v[72:75]
	v_mfma_f32_16x16x32_bf16 v[76:79], v[196:199], v[232:235], v[76:79]
	v_mfma_f32_16x16x32_bf16 v[80:83], v[200:203], v[144:147], v[80:83]
	v_mfma_f32_16x16x32_bf16 v[84:87], v[200:203], v[148:151], v[84:87]
	v_mfma_f32_16x16x32_bf16 v[88:91], v[200:203], v[228:231], v[88:91]
	v_mfma_f32_16x16x32_bf16 v[92:95], v[200:203], v[232:235], v[92:95]
	v_mfma_f32_16x16x32_bf16 v[96:99], v[204:207], v[144:147], v[96:99]
	v_mfma_f32_16x16x32_bf16 v[100:103], v[204:207], v[148:151], v[100:103]
	v_mfma_f32_16x16x32_bf16 v[104:107], v[204:207], v[228:231], v[104:107]
	v_mfma_f32_16x16x32_bf16 v[108:111], v[204:207], v[232:235], v[108:111]
	v_mfma_f32_16x16x32_bf16 v[112:115], v[208:211], v[144:147], v[112:115]
	v_mfma_f32_16x16x32_bf16 v[116:119], v[208:211], v[148:151], v[116:119]
	v_mfma_f32_16x16x32_bf16 v[120:123], v[208:211], v[228:231], v[120:123]
	v_mfma_f32_16x16x32_bf16 v[124:127], v[208:211], v[232:235], v[124:127]
	s_setprio 0
	s_add_u32 s0, s0, 0x46000
	s_addc_u32 s1, s1, 0
	s_add_u32 s4, s4, 0x120000
	s_addc_u32 s5, s5, 0
	s_add_i32 s21, s21, 1
	s_waitcnt lgkmcnt(0)
; #define RAW_BARRIER() do { asm volatile("s_waitcnt lgkmcnt(0)" ::: "memory"); __builtin_amdgcn_s_barrier(); } while (0)
; #define GEMM_WAIT4(FA, FB) asm volatile("s_waitcnt lgkmcnt(0)" : "+v"(FA[0]), "+v"(FA[1]), "+v"(FA[2]), "+v"(FA[3]), "+v"(FB[0]), "+v"(FB[1]) :: "memory")
; #define GEMM_WAIT2(FA, FB) asm volatile("s_waitcnt lgkmcnt(0)" : "+v"(FA[0]), "+v"(FA[1]), "+v"(FB[0]), "+v"(FB[1]) :: "memory")
; #define GEMM_MMA(FA, FB) do { __builtin_amdgcn_s_setprio(1); \
;       _Pragma("unroll") for (int mi = 0; mi < WM; ++mi) _Pragma("unroll") for (int ni = 0; ni < 2; ++ni) acc[mi][ni] = MFMA32(FA[mi], FB[ni], acc[mi][ni]); \
;       __builtin_amdgcn_s_setprio(0); } while (0)
; template <int WM, class Epi>
; DI void gemm_mfma(const bf16_t* __restrict__ A, const bf16_t* __restrict__ Bt, int Arows, int Brows, int MT, int NT, unsigned char* smem, int bid, int nb, int wave, Epi epi) {
;     ...
;     if constexpr (WM == 4) GEMM_WAIT4(fa1, fb1); else GEMM_WAIT2(fa1, fb1);
;     GEMM_MMA(fa1, fb1);
;     int r2 = r, h2 = h;
;     asm volatile("" : "+v"(r2), "+v"(h2));
;     epi(mt, nt, wm, wn, r2, h2, acc);
;   }
; }
;   DI void operator()(int mt, int nt, int wm, int wn, int r, int h, f32x16 (&acc)[WM][2]) const {
;     constexpr int LD = 132;
;     float* T = (float*)smem;
;     const int tid = wm * 128 + wn * 64 + h * 32 + r;
; #pragma unroll
;     for (int ps = 0; ps < WM / 2; ++ps) {
;       RAW_BARRIER();
; #pragma unroll
;       for (int mh = 0; mh < 2; ++mh)
; #pragma unroll
;         for (int ni = 0; ni < 2; ++ni)
; #pragma unroll
;           for (int i = 0; i < 16; ++i)
;             T[(wm * 64 + mh * 32 + (i & 3) + 8 * (i >> 2) + 4 * h) * LD + wn * 64 + ni * 32 + r] = acc[ps * 2 + mh][ni][i];
;       RAW_BARRIER();
;       const int ropemode0 = (nt < 4) ? 1 : ((nt >= 14 && nt <= 16) ? 2 : 0);
	s_setprio 1
	v_mfma_f32_16x16x32_bf16 v[0:3], v[128:131], v[144:147], v[0:3]
	v_mfma_f32_16x16x32_bf16 v[4:7], v[128:131], v[148:151], v[4:7]
	v_mfma_f32_16x16x32_bf16 v[8:11], v[128:131], v[228:231], v[8:11]
	v_mfma_f32_16x16x32_bf16 v[12:15], v[128:131], v[232:235], v[12:15]
	v_mfma_f32_16x16x32_bf16 v[16:19], v[132:135], v[144:147], v[16:19]
	v_mfma_f32_16x16x32_bf16 v[20:23], v[132:135], v[148:151], v[20:23]
	v_mfma_f32_16x16x32_bf16 v[24:27], v[132:135], v[228:231], v[24:27]
	v_mfma_f32_16x16x32_bf16 v[28:31], v[132:135], v[232:235], v[28:31]
	v_mfma_f32_16x16x32_bf16 v[32:35], v[136:139], v[144:147], v[32:35]
	v_mfma_f32_16x16x32_bf16 v[36:39], v[136:139], v[148:151], v[36:39]
	v_mfma_f32_16x16x32_bf16 v[40:43], v[136:139], v[228:231], v[40:43]
	v_mfma_f32_16x16x32_bf16 v[44:47], v[136:139], v[232:235], v[44:47]
	v_mfma_f32_16x16x32_bf16 v[48:51], v[140:143], v[144:147], v[48:51]
	v_mfma_f32_16x16x32_bf16 v[52:55], v[140:143], v[148:151], v[52:55]
	v_mfma_f32_16x16x32_bf16 v[56:59], v[140:143], v[228:231], v[56:59]
	v_mfma_f32_16x16x32_bf16 v[60:63], v[140:143], v[232:235], v[60:63]
	s_setprio 0
	s_sext_i32_i16 s4, s29
	s_cmp_lt_i32 s4, 4
	s_cselect_b64 s[44:45], -1, 0
	s_sub_i32 s0, s8, 17
	s_cmp_lt_u32 s0, -3
	s_cselect_b64 s[0:1], -1, 0
	s_cmp_gt_i32 s4, 3
	s_cselect_b64 s[4:5], -1, 0
	s_and_b64 s[8:9], s[4:5], exec
	v_mov_b32_e32 v133, v157
	v_mov_b32_e32 v128, v158
	s_cselect_b32 s8, 2, 1
	v_cndmask_b32_e64 v137, 0, 1, s[4:5]
	v_bitop3_b32 v131, v133, s8, 15 bitop3:0x6c
	v_lshlrev_b32_e32 v132, 3, v131
	v_lshrrev_b32_e32 v131, v137, v133
	v_lshlrev_b32_e32 v129, 5, v128
	v_and_b32_e32 v131, 2, v131
	v_add3_u32 v204, v168, v133, v129
	v_lshl_add_u32 v134, v128, 2, v169
	v_add_u32_e32 v135, v133, v167
	v_and_b32_e32 v136, 15, v133
	s_and_b64 s[46:47], s[4:5], s[0:1]
	v_cmp_eq_u32_e64 s[4:5], 0, v131
	v_lshlrev_b32_e32 v131, 3, v133
	v_bfe_u32 v133, v133, v137, 1
	v_cmp_eq_u32_e64 s[0:1], 0, v133
	v_mul_lo_u32 v133, v134, s66
	v_lshl_add_u32 v133, v135, 2, v133
	s_waitcnt lgkmcnt(0)
	s_barrier
; #define RAW_BARRIER() do { asm volatile("s_waitcnt lgkmcnt(0)" ::: "memory"); __builtin_amdgcn_s_barrier(); } while (0)
;   DI void operator()(int mt, int nt, int wm, int wn, int r, int h, f32x16 (&acc)[WM][2]) const {
;     ...
;       RAW_BARRIER();
; #pragma unroll
;       for (int mh = 0; mh < 2; ++mh)
; #pragma unroll
;         for (int ni = 0; ni < 2; ++ni)
; #pragma unroll
;           for (int i = 0; i < 16; ++i)
;             T[(wm * 64 + mh * 32 + (i & 3) + 8 * (i >> 2) + 4 * h) * LD + wn * 64 + ni * 32 + r] = acc[ps * 2 + mh][ni][i];
;       RAW_BARRIER();
;       const int ropemode0 = (nt < 4) ? 1 : ((nt >= 14 && nt <= 16) ? 2 : 0);
; #pragma unroll
;       for (int j = 0; j < 8; ++j) {
;         const int id = tid + 256 * j;
;         const int lr = id >> 4, cc = id & 15;
;         const int row = mt * (WM * 64) + (lr >> 6) * (WM * 32) + ps * 64 + (lr & 63);
;         const int col0 = nt * 128 + cc * 8;
;         if (col0 < PW) {
;           const int t = row % NTOK;
;           const int ropemode = (t >= NCTX) ? ropemode0 : 0;
;           const float4 a0 = *(const float4*)(T + lr * LD + cc * 8), a1 = *(const float4*)(T + lr * LD + cc * 8 + 4);
;           const float4 b0 = *(const float4*)(bias + col0), b1 = *(const float4*)(bias + col0 + 4);
;           float v[8] = {a0.x + b0.x, a0.y + b0.y, a0.z + b0.z, a0.w + b0.w, a1.x + b1.x, a1.y + b1.y, a1.z + b1.z, a1.w + b1.w};
;           if (ropemode != 0) {
;             const int pc = (ropemode == 1) ? (cc ^ 1) : (cc ^ 2);
;             const float4 p0 = *(const float4*)(T + lr * LD + pc * 8), p1 = *(const float4*)(T + lr * LD + pc * 8 + 4);
;             const float4 c0 = *(const float4*)(bias + nt * 128 + pc * 8), c1 = *(const float4*)(bias + nt * 128 + pc * 8 + 4);
	s_waitcnt vmcnt(0)
	v_lshrrev_b32_e32 v196, 4, v157
	v_lshl_or_b32 v196, v158, 1, v196
	v_lshrrev_b32_e32 v197, 1, v156
	v_lshlrev_b32_e32 v197, 6, v197
	v_lshl_add_u32 v196, v196, 2, v197
	v_mul_u32_u24_e32 v196, 0x210, v196
	v_and_b32_e32 v197, 1, v156
	v_lshl_add_u32 v196, v197, 8, v196
	v_and_b32_e32 v197, 15, v157
	v_lshl_add_u32 v133, v197, 2, v196
	ds_write_b32 v133, v64
	ds_write_b32 v133, v68 offset:64
	ds_write_b32 v133, v72 offset:128
	ds_write_b32 v133, v76 offset:192
	ds_write_b32 v133, v65 offset:528
	ds_write_b32 v133, v69 offset:592
	ds_write_b32 v133, v73 offset:656
	ds_write_b32 v133, v77 offset:720
	ds_write_b32 v133, v66 offset:1056
	ds_write_b32 v133, v70 offset:1120
	ds_write_b32 v133, v74 offset:1184
	ds_write_b32 v133, v78 offset:1248
	ds_write_b32 v133, v67 offset:1584
	ds_write_b32 v133, v71 offset:1648
	ds_write_b32 v133, v75 offset:1712
	ds_write_b32 v133, v79 offset:1776
	ds_write_b32 v133, v80 offset:8448
	ds_write_b32 v133, v84 offset:8512
	ds_write_b32 v133, v88 offset:8576
	ds_write_b32 v133, v92 offset:8640
	ds_write_b32 v133, v81 offset:8976
	ds_write_b32 v133, v85 offset:9040
	ds_write_b32 v133, v89 offset:9104
	ds_write_b32 v133, v93 offset:9168
	ds_write_b32 v133, v82 offset:9504
	ds_write_b32 v133, v86 offset:9568
	ds_write_b32 v133, v90 offset:9632
	ds_write_b32 v133, v94 offset:9696
	ds_write_b32 v133, v83 offset:10032
	ds_write_b32 v133, v87 offset:10096
	ds_write_b32 v133, v91 offset:10160
	ds_write_b32 v133, v95 offset:10224
	ds_write_b32 v133, v96 offset:16896
	ds_write_b32 v133, v100 offset:16960
	ds_write_b32 v133, v104 offset:17024
	ds_write_b32 v133, v108 offset:17088
	ds_write_b32 v133, v97 offset:17424
	ds_write_b32 v133, v101 offset:17488
	ds_write_b32 v133, v105 offset:17552
	ds_write_b32 v133, v109 offset:17616
	ds_write_b32 v133, v98 offset:17952
	ds_write_b32 v133, v102 offset:18016
	ds_write_b32 v133, v106 offset:18080
	ds_write_b32 v133, v110 offset:18144
	ds_write_b32 v133, v99 offset:18480
	ds_write_b32 v133, v103 offset:18544
	ds_write_b32 v133, v107 offset:18608
	ds_write_b32 v133, v111 offset:18672
	ds_write_b32 v133, v112 offset:25344
	ds_write_b32 v133, v116 offset:25408
	ds_write_b32 v133, v120 offset:25472
	ds_write_b32 v133, v124 offset:25536
	ds_write_b32 v133, v113 offset:25872
	ds_write_b32 v133, v117 offset:25936
	ds_write_b32 v133, v121 offset:26000
	ds_write_b32 v133, v125 offset:26064
	ds_write_b32 v133, v114 offset:26400
	ds_write_b32 v133, v118 offset:26464
	ds_write_b32 v133, v122 offset:26528
	ds_write_b32 v133, v126 offset:26592
	ds_write_b32 v133, v115 offset:26928
	ds_write_b32 v133, v119 offset:26992
	ds_write_b32 v133, v123 offset:27056
	ds_write_b32 v133, v127 offset:27120
	v_lshlrev_b32_e32 v130, 3, v136
	v_cmp_gt_u32_e32 vcc, 2, v136
	v_add_u32_e32 v134, 0x5800, v133
	v_add_u32_e32 v135, 0x6000, v133
	v_add_u32_e32 v136, 0x6400, v133
	v_add_u32_e32 v137, 0x6800, v133
	v_add_u32_e32 v139, 0x7200, v133
	v_add_u32_e32 v141, 0x7400, v133
	v_add_u32_e32 v142, 0x7600, v133
	v_add_u32_e32 v143, 0x7800, v133
	s_ashr_i32 s25, s24, 31
	s_and_b32 s43, 0xffff, s29
	v_or_b32_e32 v128, s24, v130
	s_cmp_eq_u32 s43, 24
	s_waitcnt lgkmcnt(0)
	v_ashrrev_i32_e32 v94, 4, v204
	v_ashrrev_i32_e32 v64, 3, v204
	v_ashrrev_i32_e32 v129, 31, v128
	s_cselect_b64 s[8:9], -1, 0
	v_and_b32_e32 v144, 0xffffff80, v64
	v_mul_lo_u32 v102, v94, s66
	v_cmp_gt_i32_e64 s[6:7], s63, v128
	v_and_b32_e32 v131, 8, v131
	s_and_b64 s[40:41], s[8:9], vcc
	v_add_u32_e32 v205, s28, v144
	v_and_b32_e32 v110, 63, v94
	v_lshl_add_u32 v111, v130, 2, v102
	v_lshl_add_u64 v[88:89], v[128:129], 2, s[14:15]
	s_barrier
	s_and_saveexec_b64 s[8:9], s[6:7]
	s_cbranch_execz .LBB0_180
	global_load_dwordx4 v[220:223], v[88:89], off
	global_load_dwordx4 v[224:227], v[88:89], off offset:16
	v_or_b32_e32 v90, v205, v110
	v_mul_hi_i32 v80, v90, s55
	ds_read_b128 v[68:71], v111
	ds_read_b128 v[76:79], v111 offset:16
	v_lshrrev_b32_e32 v81, 31, v80
	v_ashrrev_i32_e32 v80, 9, v80
	v_add_u32_e32 v80, v80, v81
	v_mul_i32_i24_e32 v80, 0x900, v80
	v_sub_u32_e32 v91, v90, v80
	s_xor_b64 s[20:21], s[46:47], -1
	v_cmp_lt_i32_e32 vcc, s62, v91
	s_and_b64 s[26:27], vcc, s[20:21]
	s_waitcnt vmcnt(0) lgkmcnt(0)
	v_pk_add_f32 v[68:69], v[68:69], v[220:221]
	v_pk_add_f32 v[70:71], v[70:71], v[222:223]
	v_pk_add_f32 v[64:65], v[76:77], v[224:225]
	v_pk_add_f32 v[66:67], v[78:79], v[226:227]
	s_and_saveexec_b64 s[20:21], s[26:27]
	s_cbranch_execz .LBB0_178
	s_lshl_b64 s[26:27], s[24:25], 2
	s_add_u32 s26, s14, s26
	v_lshlrev_b32_e32 v76, 2, v132
	s_addc_u32 s27, s15, s27
	global_load_dwordx4 v[72:75], v76, s[26:27] offset:16
	global_load_dwordx4 v[80:83], v76, s[26:27]
	v_add_u32_e32 v76, v102, v76
	ds_read_b128 v[84:87], v76
	ds_read_b128 v[76:79], v76 offset:16
	v_add_u32_e32 v92, 0xffffff00, v91
	v_lshrrev_b32_e32 v92, 6, v92
	v_and_b32_e32 v91, 63, v91
	v_cndmask_b32_e64 v91, v91, v92, s[4:5]
	s_andn2_b64 vcc, exec, s[44:45]
	s_mov_b64 s[26:27], -1
	s_cbranch_vccnz .LBB0_175
	v_lshlrev_b32_e32 v160, 6, v91
	v_lshl_add_u64 v[92:93], s[18:19], 0, v[160:161]
	s_mov_b64 s[26:27], 0

;   DI void operator()(int mt, int nt, int wm, int wn, int r, int h, f32x16 (&acc)[WM][2]) const {
;     ...
;           if (ropemode != 0) {
;             const int pc = (ropemode == 1) ? (cc ^ 1) : (cc ^ 2);
;             const float4 p0 = *(const float4*)(T + lr * LD + pc * 8), p1 = *(const float4*)(T + lr * LD + pc * 8 + 4);
;             const float4 c0 = *(const float4*)(bias + nt * 128 + pc * 8), c1 = *(const float4*)(bias + nt * 128 + pc * 8 + 4);
;             const float pr[8] = {p0.x + c0.x, p0.y + c0.y, p0.z + c0.z, p0.w + c0.w, p1.x + c1.x, p1.y + c1.y, p1.z + c1.z, p1.w + c1.w};
;             const int tok = t - NCTX;
;             const int q = (ropemode == 1) ? (cc & 3) : ((cc & 7) >> 1);
;             const int pos = (q < 2) ? (tok >> 6) : (tok & 63);
;             const float2* tab = (ropemode == 1) ? (T32 + pos * 8) : (T64 + pos * 16 + (cc & 1) * 8);
;             const float sgn = (q & 1) ? 1.f : -1.f;
; #pragma unroll
;             for (int k = 0; k < 8; ++k) { const float2 cs = tab[k]; v[k] = v[k] * cs.x + sgn * pr[k] * cs.y; }
.LBB0_177:
	global_load_dwordx4 v[228:231], v[92:93], off
	global_load_dwordx4 v[232:235], v[92:93], off offset:16
	global_load_dwordx4 v[236:239], v[92:93], off offset:32
	global_load_dwordx4 v[240:243], v[92:93], off offset:48
	v_add_u32_e32 v122, 0x100, v204
	v_ashrrev_i32_e32 v124, 4, v122
	v_ashrrev_i32_e32 v122, 3, v122
	v_and_b32_e32 v122, 0xffffff80, v122
	v_and_b32_e32 v124, 63, v124
	v_add_u32_e32 v122, s28, v122
	v_or_b32_e32 v122, v122, v124
	v_mul_hi_i32 v124, v122, s55
	v_lshrrev_b32_e32 v160, 31, v124
	v_ashrrev_i32_e32 v124, 9, v124
	v_add_u32_e32 v124, v124, v160
	v_mul_i32_i24_e32 v124, 0x900, v124
	v_sub_u32_e32 v122, v122, v124
	v_add_u32_e32 v124, 0xffffff00, v122
	v_lshrrev_b32_e32 v124, 6, v124
	v_and_b32_e32 v122, 63, v122
	v_cndmask_b32_e64 v122, v122, v124, s[4:5]
	s_andn2_b64 vcc, exec, s[44:45]
	s_cbranch_vccnz .Lrp_b_0_0
	v_lshlrev_b32_e32 v160, 6, v122
	v_lshl_add_u64 v[120:121], s[18:19], 0, v[160:161]
	s_branch .Lrp_l_0_0
.Lrp_b_0_0:
	v_lshlrev_b32_e32 v160, 4, v122
	v_lshl_add_u64 v[120:121], v[160:161], 3, s[22:23]
	v_lshlrev_b32_e32 v160, 3, v131
	v_lshl_add_u64 v[120:121], v[120:121], 0, v[160:161]
.Lrp_l_0_0:
	global_load_dwordx4 v[112:115], v[120:121], off
	global_load_dwordx4 v[116:119], v[120:121], off offset:16
	global_load_dwordx4 v[214:217], v[120:121], off offset:32
	global_load_dwordx4 v[246:249], v[120:121], off offset:48
	s_waitcnt vmcnt(4) lgkmcnt(1)
	v_mov_b32_e32 v213, v80
	v_mov_b32_e32 v218, v81
	v_mov_b32_e32 v219, v82
	v_mov_b32_e32 v245, v83
	v_mov_b32_e32 v250, v72
	v_mov_b32_e32 v251, v73
	v_mov_b32_e32 v126, v74
	v_mov_b32_e32 v127, v75
	v_add_f32_e32 v80, v84, v80
	v_add_f32_e32 v81, v85, v81
	v_add_f32_e32 v84, v86, v82
	v_add_f32_e32 v85, v87, v83
	s_waitcnt lgkmcnt(0)
	v_add_f32_e32 v86, v76, v72
	v_add_f32_e32 v87, v77, v73
	v_add_f32_e32 v91, v78, v74
	v_add_f32_e32 v95, v79, v75
	v_mov_b32_e32 v72, v228
	v_mov_b32_e32 v73, v229
	v_mov_b32_e32 v74, v230
	v_mov_b32_e32 v75, v231
	v_mov_b32_e32 v79, v69
	v_cndmask_b32_e64 v78, v80, -v80, s[0:1]
	v_cndmask_b32_e64 v84, v84, -v84, s[0:1]
	v_cndmask_b32_e64 v86, v86, -v86, s[0:1]
	s_waitcnt vmcnt(4) lgkmcnt(0)
	v_mov_b32_e32 v76, v73
	v_cndmask_b32_e64 v73, v81, -v81, s[0:1]
	v_mov_b32_e32 v69, v73
	v_mov_b32_e32 v73, v75
	v_mov_b32_e32 v77, v74
	v_pk_mul_f32 v[80:81], v[68:69], v[72:73]
	v_mov_b32_e32 v72, v232
	v_mov_b32_e32 v73, v233
	v_mov_b32_e32 v74, v234
	v_mov_b32_e32 v75, v235
	v_cndmask_b32_e64 v68, v85, -v85, s[0:1]
	v_mov_b32_e32 v85, v71
	v_mov_b32_e32 v71, v68
	s_waitcnt vmcnt(4) lgkmcnt(0)
	v_mov_b32_e32 v82, v73
	v_mov_b32_e32 v73, v75
	v_pk_mul_f32 v[72:73], v[70:71], v[72:73]
	v_mov_b32_e32 v68, v236
	v_mov_b32_e32 v69, v237
	v_mov_b32_e32 v70, v238
	v_mov_b32_e32 v71, v239
	v_mov_b32_e32 v83, v74
	s_waitcnt vmcnt(4) lgkmcnt(0)
	v_mov_b32_e32 v74, v69
	v_cndmask_b32_e64 v69, v87, -v87, s[0:1]
	v_mov_b32_e32 v87, v65
	v_mov_b32_e32 v65, v69
	v_mov_b32_e32 v69, v71
	v_mov_b32_e32 v75, v70
	v_pk_mul_f32 v[64:65], v[64:65], v[68:69]
	v_mov_b32_e32 v68, v240
	v_mov_b32_e32 v69, v241
	v_mov_b32_e32 v70, v242
	v_mov_b32_e32 v71, v243
	v_pk_fma_f32 v[64:65], v[86:87], v[74:75], v[64:65]
	s_waitcnt vmcnt(4) lgkmcnt(0)
	v_mul_f32_e32 v66, v66, v68
	v_cndmask_b32_e64 v68, v91, -v91, s[0:1]
	v_mul_f32_e32 v92, v68, v69
	v_cndmask_b32_e64 v69, v95, -v95, s[0:1]
	v_mov_b32_e32 v68, v67
	v_pk_mul_f32 v[68:69], v[68:69], v[70:71]
	v_pk_fma_f32 v[70:71], v[84:85], v[82:83], v[72:73]
	v_mov_b32_e32 v67, v68
	v_mov_b32_e32 v93, v69
	v_pk_fma_f32 v[68:69], v[78:79], v[76:77], v[80:81]
	v_pk_add_f32 v[66:67], v[66:67], v[92:93]

;   DI void operator()(int mt, int nt, int wm, int wn, int r, int h, f32x16 (&acc)[WM][2]) const {
;     ...
;         const int id = tid + 256 * j;
;         const int lr = id >> 4, cc = id & 15;
;         const int row = mt * (WM * 64) + (lr >> 6) * (WM * 32) + ps * 64 + (lr & 63);
;         const int col0 = nt * 128 + cc * 8;
;         if (col0 < PW) {
;           const int t = row % NTOK;
;           const int ropemode = (t >= NCTX) ? ropemode0 : 0;
;           const float4 a0 = *(const float4*)(T + lr * LD + cc * 8), a1 = *(const float4*)(T + lr * LD + cc * 8 + 4);
;           const float4 b0 = *(const float4*)(bias + col0), b1 = *(const float4*)(bias + col0 + 4);
;           float v[8] = {a0.x + b0.x, a0.y + b0.y, a0.z + b0.z, a0.w + b0.w, a1.x + b1.x, a1.y + b1.y, a1.z + b1.z, a1.w + b1.w};
;           if (ropemode != 0) {
;             const int pc = (ropemode == 1) ? (cc ^ 1) : (cc ^ 2);
;             const float4 p0 = *(const float4*)(T + lr * LD + pc * 8), p1 = *(const float4*)(T + lr * LD + pc * 8 + 4);
;             const float4 c0 = *(const float4*)(bias + nt * 128 + pc * 8), c1 = *(const float4*)(bias + nt * 128 + pc * 8 + 4);
.LBB0_180:
	s_or_b64 exec, exec, s[8:9]
	s_nop 0
	v_add_u32_e32 v64, 0x100, v204
	v_ashrrev_i32_e32 v95, 4, v64
	v_ashrrev_i32_e32 v64, 3, v64
	v_and_b32_e32 v147, 0xffffff80, v64
	v_mul_lo_u32 v103, v95, s66
	v_add_u32_e32 v206, s28, v147
	v_and_b32_e32 v123, 63, v95
	v_lshl_add_u32 v125, v130, 2, v103
	s_and_saveexec_b64 s[8:9], s[6:7]
	s_cbranch_execz .LBB0_189
	v_or_b32_e32 v90, v206, v123
	v_mul_hi_i32 v80, v90, s55
	ds_read_b128 v[68:71], v125
	ds_read_b128 v[76:79], v125 offset:16
	v_lshrrev_b32_e32 v81, 31, v80
	v_ashrrev_i32_e32 v80, 9, v80
	v_add_u32_e32 v80, v80, v81
	v_mul_i32_i24_e32 v80, 0x900, v80
	v_sub_u32_e32 v91, v90, v80
	s_xor_b64 s[20:21], s[46:47], -1
	v_cmp_lt_i32_e32 vcc, s62, v91
	s_and_b64 s[26:27], vcc, s[20:21]
	s_waitcnt lgkmcnt(0)
	v_pk_add_f32 v[68:69], v[68:69], v[220:221]
	v_pk_add_f32 v[70:71], v[70:71], v[222:223]
	v_pk_add_f32 v[64:65], v[76:77], v[224:225]
	v_pk_add_f32 v[66:67], v[78:79], v[226:227]
	s_and_saveexec_b64 s[20:21], s[26:27]
	s_cbranch_execz .LBB0_187
	s_lshl_b64 s[26:27], s[24:25], 2
	s_add_u32 s26, s14, s26
	v_lshlrev_b32_e32 v76, 2, v132
	s_addc_u32 s27, s15, s27
	v_add_u32_e32 v76, v103, v76
	ds_read_b128 v[84:87], v76
	ds_read_b128 v[76:79], v76 offset:16
	v_add_u32_e32 v92, 0xffffff00, v91
	v_lshrrev_b32_e32 v92, 6, v92
	v_and_b32_e32 v91, 63, v91
	v_cndmask_b32_e64 v91, v91, v92, s[4:5]
	s_andn2_b64 vcc, exec, s[44:45]
	s_mov_b64 s[26:27], -1
	s_cbranch_vccnz .LBB0_184
	v_lshlrev_b32_e32 v160, 6, v91
	v_lshl_add_u64 v[92:93], s[18:19], 0, v[160:161]
	s_mov_b64 s[26:27], 0

;   DI void operator()(int mt, int nt, int wm, int wn, int r, int h, f32x16 (&acc)[WM][2]) const {
;     ...
;             const float pr[8] = {p0.x + c0.x, p0.y + c0.y, p0.z + c0.z, p0.w + c0.w, p1.x + c1.x, p1.y + c1.y, p1.z + c1.z, p1.w + c1.w};
;             const int tok = t - NCTX;
;             const int q = (ropemode == 1) ? (cc & 3) : ((cc & 7) >> 1);
;             const int pos = (q < 2) ? (tok >> 6) : (tok & 63);
;             const float2* tab = (ropemode == 1) ? (T32 + pos * 8) : (T64 + pos * 16 + (cc & 1) * 8);
.LBB0_186:
	v_add_u32_e32 v122, 0x200, v204
	v_ashrrev_i32_e32 v124, 4, v122
	v_ashrrev_i32_e32 v122, 3, v122
	v_and_b32_e32 v122, 0xffffff80, v122
	v_and_b32_e32 v124, 63, v124
	v_add_u32_e32 v122, s28, v122
	v_or_b32_e32 v122, v122, v124
	v_mul_hi_i32 v124, v122, s55
	v_lshrrev_b32_e32 v160, 31, v124
	v_ashrrev_i32_e32 v124, 9, v124
	v_add_u32_e32 v124, v124, v160
	v_mul_i32_i24_e32 v124, 0x900, v124
	v_sub_u32_e32 v122, v122, v124
	v_add_u32_e32 v124, 0xffffff00, v122
	v_lshrrev_b32_e32 v124, 6, v124
	v_and_b32_e32 v122, 63, v122
	v_cndmask_b32_e64 v122, v122, v124, s[4:5]
	s_andn2_b64 vcc, exec, s[44:45]
	s_cbranch_vccnz .Lrp_b_0_1
	v_lshlrev_b32_e32 v160, 6, v122
	v_lshl_add_u64 v[120:121], s[18:19], 0, v[160:161]
	s_branch .Lrp_l_0_1

;   DI void operator()(int mt, int nt, int wm, int wn, int r, int h, f32x16 (&acc)[WM][2]) const {
;     ...
;             const float pr[8] = {p0.x + c0.x, p0.y + c0.y, p0.z + c0.z, p0.w + c0.w, p1.x + c1.x, p1.y + c1.y, p1.z + c1.z, p1.w + c1.w};
;             const int tok = t - NCTX;
;             const int q = (ropemode == 1) ? (cc & 3) : ((cc & 7) >> 1);
;             const int pos = (q < 2) ? (tok >> 6) : (tok & 63);
;             const float2* tab = (ropemode == 1) ? (T32 + pos * 8) : (T64 + pos * 16 + (cc & 1) * 8);
;             const float sgn = (q & 1) ? 1.f : -1.f;
; #pragma unroll
;             for (int k = 0; k < 8; ++k) { const float2 cs = tab[k]; v[k] = v[k] * cs.x + sgn * pr[k] * cs.y; }
.Lrp_l_0_1:
	global_load_dwordx4 v[228:231], v[120:121], off
	global_load_dwordx4 v[232:235], v[120:121], off offset:16
	global_load_dwordx4 v[236:239], v[120:121], off offset:32
	global_load_dwordx4 v[240:243], v[120:121], off offset:48
	s_waitcnt vmcnt(4) lgkmcnt(1)
	v_add_f32_e32 v80, v84, v213
	v_add_f32_e32 v81, v85, v218
	v_add_f32_e32 v84, v86, v219
	v_add_f32_e32 v85, v87, v245
	s_waitcnt lgkmcnt(0)
	v_add_f32_e32 v86, v76, v250
	v_add_f32_e32 v87, v77, v251
	v_add_f32_e32 v91, v78, v126
	v_add_f32_e32 v96, v79, v127
	v_mov_b32_e32 v72, v112
	v_mov_b32_e32 v73, v113
	v_mov_b32_e32 v74, v114
	v_mov_b32_e32 v75, v115
	v_mov_b32_e32 v79, v69
	v_cndmask_b32_e64 v78, v80, -v80, s[0:1]
	v_cndmask_b32_e64 v84, v84, -v84, s[0:1]
	v_cndmask_b32_e64 v86, v86, -v86, s[0:1]
	s_waitcnt vmcnt(4) lgkmcnt(0)
	v_mov_b32_e32 v76, v73
	v_cndmask_b32_e64 v73, v81, -v81, s[0:1]
	v_mov_b32_e32 v69, v73
	v_mov_b32_e32 v73, v75
	v_mov_b32_e32 v77, v74
	v_pk_mul_f32 v[80:81], v[68:69], v[72:73]
	v_mov_b32_e32 v72, v116
	v_mov_b32_e32 v73, v117
	v_mov_b32_e32 v74, v118
	v_mov_b32_e32 v75, v119
	v_cndmask_b32_e64 v68, v85, -v85, s[0:1]
	v_mov_b32_e32 v85, v71
	v_mov_b32_e32 v71, v68
	s_waitcnt vmcnt(4) lgkmcnt(0)
	v_mov_b32_e32 v82, v73
	v_mov_b32_e32 v73, v75
	v_pk_mul_f32 v[72:73], v[70:71], v[72:73]
	v_mov_b32_e32 v68, v214
	v_mov_b32_e32 v69, v215
	v_mov_b32_e32 v70, v216
	v_mov_b32_e32 v71, v217
	v_mov_b32_e32 v83, v74
	s_waitcnt vmcnt(4) lgkmcnt(0)
	v_mov_b32_e32 v74, v69
	v_cndmask_b32_e64 v69, v87, -v87, s[0:1]
	v_mov_b32_e32 v87, v65
	v_mov_b32_e32 v65, v69
	v_mov_b32_e32 v69, v71
	v_mov_b32_e32 v75, v70
	v_pk_mul_f32 v[64:65], v[64:65], v[68:69]
	v_mov_b32_e32 v68, v246
	v_mov_b32_e32 v69, v247
	v_mov_b32_e32 v70, v248
	v_mov_b32_e32 v71, v249
	v_pk_fma_f32 v[64:65], v[86:87], v[74:75], v[64:65]
	s_waitcnt vmcnt(4) lgkmcnt(0)
	v_mul_f32_e32 v66, v66, v68
	v_cndmask_b32_e64 v68, v91, -v91, s[0:1]
	v_mul_f32_e32 v92, v68, v69
	v_cndmask_b32_e64 v69, v96, -v96, s[0:1]
	v_mov_b32_e32 v68, v67
	v_pk_mul_f32 v[68:69], v[68:69], v[70:71]
	v_pk_fma_f32 v[70:71], v[84:85], v[82:83], v[72:73]
	v_mov_b32_e32 v67, v68
	v_mov_b32_e32 v93, v69
	v_pk_fma_f32 v[68:69], v[78:79], v[76:77], v[80:81]
	v_pk_add_f32 v[66:67], v[66:67], v[92:93]

;   DI void operator()(int mt, int nt, int wm, int wn, int r, int h, f32x16 (&acc)[WM][2]) const {
;     ...
;         const int id = tid + 256 * j;
;         const int lr = id >> 4, cc = id & 15;
;         const int row = mt * (WM * 64) + (lr >> 6) * (WM * 32) + ps * 64 + (lr & 63);
;         const int col0 = nt * 128 + cc * 8;
;         if (col0 < PW) {
;           const int t = row % NTOK;
;           const int ropemode = (t >= NCTX) ? ropemode0 : 0;
;           const float4 a0 = *(const float4*)(T + lr * LD + cc * 8), a1 = *(const float4*)(T + lr * LD + cc * 8 + 4);
;           const float4 b0 = *(const float4*)(bias + col0), b1 = *(const float4*)(bias + col0 + 4);
;           float v[8] = {a0.x + b0.x, a0.y + b0.y, a0.z + b0.z, a0.w + b0.w, a1.x + b1.x, a1.y + b1.y, a1.z + b1.z, a1.w + b1.w};
;           if (ropemode != 0) {
;             const int pc = (ropemode == 1) ? (cc ^ 1) : (cc ^ 2);
;             const float4 p0 = *(const float4*)(T + lr * LD + pc * 8), p1 = *(const float4*)(T + lr * LD + pc * 8 + 4);
;             const float4 c0 = *(const float4*)(bias + nt * 128 + pc * 8), c1 = *(const float4*)(bias + nt * 128 + pc * 8 + 4);
.LBB0_189:
	s_or_b64 exec, exec, s[8:9]
	s_nop 0
	v_add_u32_e32 v64, 0x200, v204
	v_ashrrev_i32_e32 v96, 4, v64
	v_ashrrev_i32_e32 v64, 3, v64
	v_and_b32_e32 v150, 0xffffff80, v64
	v_mul_lo_u32 v104, v96, s66
	v_add_u32_e32 v207, s28, v150
	v_and_b32_e32 v138, 63, v96
	v_lshl_add_u32 v140, v130, 2, v104
	s_and_saveexec_b64 s[8:9], s[6:7]
	s_cbranch_execz .LBB0_198
	v_or_b32_e32 v90, v207, v138
	v_mul_hi_i32 v80, v90, s55
	ds_read_b128 v[68:71], v140
	ds_read_b128 v[76:79], v140 offset:16
	v_lshrrev_b32_e32 v81, 31, v80
	v_ashrrev_i32_e32 v80, 9, v80
	v_add_u32_e32 v80, v80, v81
	v_mul_i32_i24_e32 v80, 0x900, v80
	v_sub_u32_e32 v91, v90, v80
	s_xor_b64 s[20:21], s[46:47], -1
	v_cmp_lt_i32_e32 vcc, s62, v91
	s_and_b64 s[26:27], vcc, s[20:21]
	s_waitcnt lgkmcnt(0)
	v_pk_add_f32 v[68:69], v[68:69], v[220:221]
	v_pk_add_f32 v[70:71], v[70:71], v[222:223]
	v_pk_add_f32 v[64:65], v[76:77], v[224:225]
	v_pk_add_f32 v[66:67], v[78:79], v[226:227]
	s_and_saveexec_b64 s[20:21], s[26:27]
	s_cbranch_execz .LBB0_196
	s_lshl_b64 s[26:27], s[24:25], 2
	s_add_u32 s26, s14, s26
	v_lshlrev_b32_e32 v76, 2, v132
	s_addc_u32 s27, s15, s27
	v_add_u32_e32 v76, v104, v76
	ds_read_b128 v[84:87], v76
	ds_read_b128 v[76:79], v76 offset:16
	v_add_u32_e32 v92, 0xffffff00, v91
	v_lshrrev_b32_e32 v92, 6, v92
	v_and_b32_e32 v91, 63, v91
	v_cndmask_b32_e64 v91, v91, v92, s[4:5]
	s_andn2_b64 vcc, exec, s[44:45]
	s_mov_b64 s[26:27], -1
	s_cbranch_vccnz .LBB0_193
	v_lshlrev_b32_e32 v160, 6, v91
	v_lshl_add_u64 v[92:93], s[18:19], 0, v[160:161]
	s_mov_b64 s[26:27], 0

;   DI void operator()(int mt, int nt, int wm, int wn, int r, int h, f32x16 (&acc)[WM][2]) const {
;     ...
;             const float pr[8] = {p0.x + c0.x, p0.y + c0.y, p0.z + c0.z, p0.w + c0.w, p1.x + c1.x, p1.y + c1.y, p1.z + c1.z, p1.w + c1.w};
;             const int tok = t - NCTX;
;             const int q = (ropemode == 1) ? (cc & 3) : ((cc & 7) >> 1);
;             const int pos = (q < 2) ? (tok >> 6) : (tok & 63);
;             const float2* tab = (ropemode == 1) ? (T32 + pos * 8) : (T64 + pos * 16 + (cc & 1) * 8);
.LBB0_195:
	v_add_u32_e32 v122, 0x300, v204
	v_ashrrev_i32_e32 v124, 4, v122
	v_ashrrev_i32_e32 v122, 3, v122
	v_and_b32_e32 v122, 0xffffff80, v122
	v_and_b32_e32 v124, 63, v124
	v_add_u32_e32 v122, s28, v122
	v_or_b32_e32 v122, v122, v124
	v_mul_hi_i32 v124, v122, s55
	v_lshrrev_b32_e32 v160, 31, v124
	v_ashrrev_i32_e32 v124, 9, v124
	v_add_u32_e32 v124, v124, v160
	v_mul_i32_i24_e32 v124, 0x900, v124
	v_sub_u32_e32 v122, v122, v124
	v_add_u32_e32 v124, 0xffffff00, v122
	v_lshrrev_b32_e32 v124, 6, v124
	v_and_b32_e32 v122, 63, v122
	v_cndmask_b32_e64 v122, v122, v124, s[4:5]
	s_andn2_b64 vcc, exec, s[44:45]
	s_cbranch_vccnz .Lrp_b_0_2
	v_lshlrev_b32_e32 v160, 6, v122
	v_lshl_add_u64 v[120:121], s[18:19], 0, v[160:161]
	s_branch .Lrp_l_0_2

;   DI void operator()(int mt, int nt, int wm, int wn, int r, int h, f32x16 (&acc)[WM][2]) const {
;     ...
;             const float pr[8] = {p0.x + c0.x, p0.y + c0.y, p0.z + c0.z, p0.w + c0.w, p1.x + c1.x, p1.y + c1.y, p1.z + c1.z, p1.w + c1.w};
;             const int tok = t - NCTX;
;             const int q = (ropemode == 1) ? (cc & 3) : ((cc & 7) >> 1);
;             const int pos = (q < 2) ? (tok >> 6) : (tok & 63);
;             const float2* tab = (ropemode == 1) ? (T32 + pos * 8) : (T64 + pos * 16 + (cc & 1) * 8);
;             const float sgn = (q & 1) ? 1.f : -1.f;
; #pragma unroll
;             for (int k = 0; k < 8; ++k) { const float2 cs = tab[k]; v[k] = v[k] * cs.x + sgn * pr[k] * cs.y; }
.Lrp_l_0_2:
	global_load_dwordx4 v[112:115], v[120:121], off
	global_load_dwordx4 v[116:119], v[120:121], off offset:16
	global_load_dwordx4 v[214:217], v[120:121], off offset:32
	global_load_dwordx4 v[246:249], v[120:121], off offset:48
	s_waitcnt vmcnt(4) lgkmcnt(1)
	v_add_f32_e32 v80, v84, v213
	v_add_f32_e32 v81, v85, v218
	v_add_f32_e32 v84, v86, v219
	v_add_f32_e32 v85, v87, v245
	s_waitcnt lgkmcnt(0)
	v_add_f32_e32 v86, v76, v250
	v_add_f32_e32 v87, v77, v251
	v_add_f32_e32 v91, v78, v126
	v_add_f32_e32 v97, v79, v127
	v_mov_b32_e32 v72, v228
	v_mov_b32_e32 v73, v229
	v_mov_b32_e32 v74, v230
	v_mov_b32_e32 v75, v231
	v_mov_b32_e32 v79, v69
	v_cndmask_b32_e64 v78, v80, -v80, s[0:1]
	v_cndmask_b32_e64 v84, v84, -v84, s[0:1]
	v_cndmask_b32_e64 v86, v86, -v86, s[0:1]
	s_waitcnt vmcnt(4) lgkmcnt(0)
	v_mov_b32_e32 v76, v73
	v_cndmask_b32_e64 v73, v81, -v81, s[0:1]
	v_mov_b32_e32 v69, v73
	v_mov_b32_e32 v73, v75
	v_mov_b32_e32 v77, v74
	v_pk_mul_f32 v[80:81], v[68:69], v[72:73]
	v_mov_b32_e32 v72, v232
	v_mov_b32_e32 v73, v233
	v_mov_b32_e32 v74, v234
	v_mov_b32_e32 v75, v235
	v_cndmask_b32_e64 v68, v85, -v85, s[0:1]
	v_mov_b32_e32 v85, v71
	v_mov_b32_e32 v71, v68
	s_waitcnt vmcnt(4) lgkmcnt(0)
	v_mov_b32_e32 v82, v73
	v_mov_b32_e32 v73, v75
	v_pk_mul_f32 v[72:73], v[70:71], v[72:73]
	v_mov_b32_e32 v68, v236
	v_mov_b32_e32 v69, v237
	v_mov_b32_e32 v70, v238
	v_mov_b32_e32 v71, v239
	v_mov_b32_e32 v83, v74
	s_waitcnt vmcnt(4) lgkmcnt(0)
	v_mov_b32_e32 v74, v69
	v_cndmask_b32_e64 v69, v87, -v87, s[0:1]
	v_mov_b32_e32 v87, v65
	v_mov_b32_e32 v65, v69
	v_mov_b32_e32 v69, v71
	v_mov_b32_e32 v75, v70
	v_pk_mul_f32 v[64:65], v[64:65], v[68:69]
	v_mov_b32_e32 v68, v240
	v_mov_b32_e32 v69, v241
	v_mov_b32_e32 v70, v242
	v_mov_b32_e32 v71, v243
	v_pk_fma_f32 v[64:65], v[86:87], v[74:75], v[64:65]
	s_waitcnt vmcnt(4) lgkmcnt(0)
	v_mul_f32_e32 v66, v66, v68
	v_cndmask_b32_e64 v68, v91, -v91, s[0:1]
	v_mul_f32_e32 v92, v68, v69
	v_cndmask_b32_e64 v69, v97, -v97, s[0:1]
	v_mov_b32_e32 v68, v67
	v_pk_mul_f32 v[68:69], v[68:69], v[70:71]
	v_pk_fma_f32 v[70:71], v[84:85], v[82:83], v[72:73]
	v_mov_b32_e32 v67, v68
	v_mov_b32_e32 v93, v69
	v_pk_fma_f32 v[68:69], v[78:79], v[76:77], v[80:81]
	v_pk_add_f32 v[66:67], v[66:67], v[92:93]

;   DI void operator()(int mt, int nt, int wm, int wn, int r, int h, f32x16 (&acc)[WM][2]) const {
;     ...
;         const int id = tid + 256 * j;
;         const int lr = id >> 4, cc = id & 15;
;         const int row = mt * (WM * 64) + (lr >> 6) * (WM * 32) + ps * 64 + (lr & 63);
;         const int col0 = nt * 128 + cc * 8;
;         if (col0 < PW) {
;           const int t = row % NTOK;
;           const int ropemode = (t >= NCTX) ? ropemode0 : 0;
;           const float4 a0 = *(const float4*)(T + lr * LD + cc * 8), a1 = *(const float4*)(T + lr * LD + cc * 8 + 4);
;           const float4 b0 = *(const float4*)(bias + col0), b1 = *(const float4*)(bias + col0 + 4);
;           float v[8] = {a0.x + b0.x, a0.y + b0.y, a0.z + b0.z, a0.w + b0.w, a1.x + b1.x, a1.y + b1.y, a1.z + b1.z, a1.w + b1.w};
;           if (ropemode != 0) {
;             const int pc = (ropemode == 1) ? (cc ^ 1) : (cc ^ 2);
;             const float4 p0 = *(const float4*)(T + lr * LD + pc * 8), p1 = *(const float4*)(T + lr * LD + pc * 8 + 4);
;             const float4 c0 = *(const float4*)(bias + nt * 128 + pc * 8), c1 = *(const float4*)(bias + nt * 128 + pc * 8 + 4);
.LBB0_198:
	s_or_b64 exec, exec, s[8:9]
	s_nop 0
	v_add_u32_e32 v64, 0x300, v204
	v_ashrrev_i32_e32 v97, 4, v64
	v_ashrrev_i32_e32 v64, 3, v64
	v_and_b32_e32 v171, 0xffffff80, v64
	v_mul_lo_u32 v105, v97, s66
	v_add_u32_e32 v208, s28, v171
	v_and_b32_e32 v145, 63, v97
	v_lshl_add_u32 v146, v130, 2, v105
	s_and_saveexec_b64 s[8:9], s[6:7]
	s_cbranch_execz .LBB0_207
	v_or_b32_e32 v90, v208, v145
	v_mul_hi_i32 v80, v90, s55
	ds_read_b128 v[68:71], v146
	ds_read_b128 v[76:79], v146 offset:16
	v_lshrrev_b32_e32 v81, 31, v80
	v_ashrrev_i32_e32 v80, 9, v80
	v_add_u32_e32 v80, v80, v81
	v_mul_i32_i24_e32 v80, 0x900, v80
	v_sub_u32_e32 v91, v90, v80
	s_xor_b64 s[20:21], s[46:47], -1
	v_cmp_lt_i32_e32 vcc, s62, v91
	s_and_b64 s[26:27], vcc, s[20:21]
	s_waitcnt lgkmcnt(0)
	v_pk_add_f32 v[68:69], v[68:69], v[220:221]
	v_pk_add_f32 v[70:71], v[70:71], v[222:223]
	v_pk_add_f32 v[64:65], v[76:77], v[224:225]
	v_pk_add_f32 v[66:67], v[78:79], v[226:227]
	s_and_saveexec_b64 s[20:21], s[26:27]
	s_cbranch_execz .LBB0_205
	s_lshl_b64 s[26:27], s[24:25], 2
	s_add_u32 s26, s14, s26
	v_lshlrev_b32_e32 v76, 2, v132
	s_addc_u32 s27, s15, s27
	v_add_u32_e32 v76, v105, v76
	ds_read_b128 v[84:87], v76
	ds_read_b128 v[76:79], v76 offset:16
	v_add_u32_e32 v92, 0xffffff00, v91
	v_lshrrev_b32_e32 v92, 6, v92
	v_and_b32_e32 v91, 63, v91
	v_cndmask_b32_e64 v91, v91, v92, s[4:5]
	s_andn2_b64 vcc, exec, s[44:45]
	s_mov_b64 s[26:27], -1
	s_cbranch_vccnz .LBB0_202
	v_lshlrev_b32_e32 v160, 6, v91
	v_lshl_add_u64 v[92:93], s[18:19], 0, v[160:161]
	s_mov_b64 s[26:27], 0

;   DI void operator()(int mt, int nt, int wm, int wn, int r, int h, f32x16 (&acc)[WM][2]) const {
;     ...
;             const float pr[8] = {p0.x + c0.x, p0.y + c0.y, p0.z + c0.z, p0.w + c0.w, p1.x + c1.x, p1.y + c1.y, p1.z + c1.z, p1.w + c1.w};
;             const int tok = t - NCTX;
;             const int q = (ropemode == 1) ? (cc & 3) : ((cc & 7) >> 1);
;             const int pos = (q < 2) ? (tok >> 6) : (tok & 63);
;             const float2* tab = (ropemode == 1) ? (T32 + pos * 8) : (T64 + pos * 16 + (cc & 1) * 8);
.LBB0_204:
	v_add_u32_e32 v122, 0x400, v204
	v_ashrrev_i32_e32 v124, 4, v122
	v_ashrrev_i32_e32 v122, 3, v122
	v_and_b32_e32 v122, 0xffffff80, v122
	v_and_b32_e32 v124, 63, v124
	v_add_u32_e32 v122, s28, v122
	v_or_b32_e32 v122, v122, v124
	v_mul_hi_i32 v124, v122, s55
	v_lshrrev_b32_e32 v160, 31, v124
	v_ashrrev_i32_e32 v124, 9, v124
	v_add_u32_e32 v124, v124, v160
	v_mul_i32_i24_e32 v124, 0x900, v124
	v_sub_u32_e32 v122, v122, v124
	v_add_u32_e32 v124, 0xffffff00, v122
	v_lshrrev_b32_e32 v124, 6, v124
	v_and_b32_e32 v122, 63, v122
	v_cndmask_b32_e64 v122, v122, v124, s[4:5]
	s_andn2_b64 vcc, exec, s[44:45]
	s_cbranch_vccnz .Lrp_b_0_3
	v_lshlrev_b32_e32 v160, 6, v122
	v_lshl_add_u64 v[120:121], s[18:19], 0, v[160:161]
	s_branch .Lrp_l_0_3

;   DI void operator()(int mt, int nt, int wm, int wn, int r, int h, f32x16 (&acc)[WM][2]) const {
;     ...
;             const float pr[8] = {p0.x + c0.x, p0.y + c0.y, p0.z + c0.z, p0.w + c0.w, p1.x + c1.x, p1.y + c1.y, p1.z + c1.z, p1.w + c1.w};
;             const int tok = t - NCTX;
;             const int q = (ropemode == 1) ? (cc & 3) : ((cc & 7) >> 1);
;             const int pos = (q < 2) ? (tok >> 6) : (tok & 63);
;             const float2* tab = (ropemode == 1) ? (T32 + pos * 8) : (T64 + pos * 16 + (cc & 1) * 8);
;             const float sgn = (q & 1) ? 1.f : -1.f;
; #pragma unroll
;             for (int k = 0; k < 8; ++k) { const float2 cs = tab[k]; v[k] = v[k] * cs.x + sgn * pr[k] * cs.y; }
.Lrp_l_0_3:
	global_load_dwordx4 v[228:231], v[120:121], off
	global_load_dwordx4 v[232:235], v[120:121], off offset:16
	global_load_dwordx4 v[236:239], v[120:121], off offset:32
	global_load_dwordx4 v[240:243], v[120:121], off offset:48
	s_waitcnt vmcnt(4) lgkmcnt(1)
	v_add_f32_e32 v80, v84, v213
	v_add_f32_e32 v81, v85, v218
	v_add_f32_e32 v84, v86, v219
	v_add_f32_e32 v85, v87, v245
	s_waitcnt lgkmcnt(0)
	v_add_f32_e32 v86, v76, v250
	v_add_f32_e32 v87, v77, v251
	v_add_f32_e32 v91, v78, v126
	v_add_f32_e32 v98, v79, v127
	v_mov_b32_e32 v72, v112
	v_mov_b32_e32 v73, v113
	v_mov_b32_e32 v74, v114
	v_mov_b32_e32 v75, v115
	v_mov_b32_e32 v79, v69
	v_cndmask_b32_e64 v78, v80, -v80, s[0:1]
	v_cndmask_b32_e64 v84, v84, -v84, s[0:1]
	v_cndmask_b32_e64 v86, v86, -v86, s[0:1]
	s_waitcnt vmcnt(4) lgkmcnt(0)
	v_mov_b32_e32 v76, v73
	v_cndmask_b32_e64 v73, v81, -v81, s[0:1]
	v_mov_b32_e32 v69, v73
	v_mov_b32_e32 v73, v75
	v_mov_b32_e32 v77, v74
	v_pk_mul_f32 v[80:81], v[68:69], v[72:73]
	v_mov_b32_e32 v72, v116
	v_mov_b32_e32 v73, v117
	v_mov_b32_e32 v74, v118
	v_mov_b32_e32 v75, v119
	v_cndmask_b32_e64 v68, v85, -v85, s[0:1]
	v_mov_b32_e32 v85, v71
	v_mov_b32_e32 v71, v68
	s_waitcnt vmcnt(4) lgkmcnt(0)
	v_mov_b32_e32 v82, v73
	v_mov_b32_e32 v73, v75
	v_pk_mul_f32 v[72:73], v[70:71], v[72:73]
	v_mov_b32_e32 v68, v214
	v_mov_b32_e32 v69, v215
	v_mov_b32_e32 v70, v216
	v_mov_b32_e32 v71, v217
	v_mov_b32_e32 v83, v74
	s_waitcnt vmcnt(4) lgkmcnt(0)
	v_mov_b32_e32 v74, v69
	v_cndmask_b32_e64 v69, v87, -v87, s[0:1]
	v_mov_b32_e32 v87, v65
	v_mov_b32_e32 v65, v69
	v_mov_b32_e32 v69, v71
	v_mov_b32_e32 v75, v70
	v_pk_mul_f32 v[64:65], v[64:65], v[68:69]
	v_mov_b32_e32 v68, v246
	v_mov_b32_e32 v69, v247
	v_mov_b32_e32 v70, v248
	v_mov_b32_e32 v71, v249
	v_pk_fma_f32 v[64:65], v[86:87], v[74:75], v[64:65]
	s_waitcnt vmcnt(4) lgkmcnt(0)
	v_mul_f32_e32 v66, v66, v68
	v_cndmask_b32_e64 v68, v91, -v91, s[0:1]
	v_mul_f32_e32 v92, v68, v69
	v_cndmask_b32_e64 v69, v98, -v98, s[0:1]
	v_mov_b32_e32 v68, v67
	v_pk_mul_f32 v[68:69], v[68:69], v[70:71]
	v_pk_fma_f32 v[70:71], v[84:85], v[82:83], v[72:73]
	v_mov_b32_e32 v67, v68
	v_mov_b32_e32 v93, v69
	v_pk_fma_f32 v[68:69], v[78:79], v[76:77], v[80:81]
	v_pk_add_f32 v[66:67], v[66:67], v[92:93]

;   DI void operator()(int mt, int nt, int wm, int wn, int r, int h, f32x16 (&acc)[WM][2]) const {
;     ...
;         const int id = tid + 256 * j;
;         const int lr = id >> 4, cc = id & 15;
;         const int row = mt * (WM * 64) + (lr >> 6) * (WM * 32) + ps * 64 + (lr & 63);
;         const int col0 = nt * 128 + cc * 8;
;         if (col0 < PW) {
;           const int t = row % NTOK;
;           const int ropemode = (t >= NCTX) ? ropemode0 : 0;
;           const float4 a0 = *(const float4*)(T + lr * LD + cc * 8), a1 = *(const float4*)(T + lr * LD + cc * 8 + 4);
;           const float4 b0 = *(const float4*)(bias + col0), b1 = *(const float4*)(bias + col0 + 4);
;           float v[8] = {a0.x + b0.x, a0.y + b0.y, a0.z + b0.z, a0.w + b0.w, a1.x + b1.x, a1.y + b1.y, a1.z + b1.z, a1.w + b1.w};
;           if (ropemode != 0) {
;             const int pc = (ropemode == 1) ? (cc ^ 1) : (cc ^ 2);
;             const float4 p0 = *(const float4*)(T + lr * LD + pc * 8), p1 = *(const float4*)(T + lr * LD + pc * 8 + 4);
;             const float4 c0 = *(const float4*)(bias + nt * 128 + pc * 8), c1 = *(const float4*)(bias + nt * 128 + pc * 8 + 4);
.LBB0_207:
	s_or_b64 exec, exec, s[8:9]
	s_nop 0
	v_add_u32_e32 v64, 0x400, v204
	v_ashrrev_i32_e32 v98, 4, v64
	v_ashrrev_i32_e32 v64, 3, v64
	v_and_b32_e32 v198, 0xffffff80, v64
	v_mul_lo_u32 v106, v98, s66
	v_add_u32_e32 v209, s28, v198
	v_and_b32_e32 v148, 63, v98
	v_lshl_add_u32 v149, v130, 2, v106
	s_and_saveexec_b64 s[8:9], s[6:7]
	s_cbranch_execz .LBB0_216
	v_or_b32_e32 v90, v209, v148
	v_mul_hi_i32 v80, v90, s55
	ds_read_b128 v[68:71], v149
	ds_read_b128 v[76:79], v149 offset:16
	v_lshrrev_b32_e32 v81, 31, v80
	v_ashrrev_i32_e32 v80, 9, v80
	v_add_u32_e32 v80, v80, v81
	v_mul_i32_i24_e32 v80, 0x900, v80
	v_sub_u32_e32 v91, v90, v80
	s_xor_b64 s[20:21], s[46:47], -1
	v_cmp_lt_i32_e32 vcc, s62, v91
	s_and_b64 s[26:27], vcc, s[20:21]
	s_waitcnt lgkmcnt(0)
	v_pk_add_f32 v[68:69], v[68:69], v[220:221]
	v_pk_add_f32 v[70:71], v[70:71], v[222:223]
	v_pk_add_f32 v[64:65], v[76:77], v[224:225]
	v_pk_add_f32 v[66:67], v[78:79], v[226:227]
	s_and_saveexec_b64 s[20:21], s[26:27]
	s_cbranch_execz .LBB0_214
	s_lshl_b64 s[26:27], s[24:25], 2
	s_add_u32 s26, s14, s26
	v_lshlrev_b32_e32 v76, 2, v132
	s_addc_u32 s27, s15, s27
	v_add_u32_e32 v76, v106, v76
	ds_read_b128 v[84:87], v76
	ds_read_b128 v[76:79], v76 offset:16
	v_add_u32_e32 v92, 0xffffff00, v91
	v_lshrrev_b32_e32 v92, 6, v92
	v_and_b32_e32 v91, 63, v91
	v_cndmask_b32_e64 v91, v91, v92, s[4:5]
	s_andn2_b64 vcc, exec, s[44:45]
	s_mov_b64 s[26:27], -1
	s_cbranch_vccnz .LBB0_211
	v_lshlrev_b32_e32 v160, 6, v91
	v_lshl_add_u64 v[92:93], s[18:19], 0, v[160:161]
	s_mov_b64 s[26:27], 0

;   DI void operator()(int mt, int nt, int wm, int wn, int r, int h, f32x16 (&acc)[WM][2]) const {
;     ...
;             const float pr[8] = {p0.x + c0.x, p0.y + c0.y, p0.z + c0.z, p0.w + c0.w, p1.x + c1.x, p1.y + c1.y, p1.z + c1.z, p1.w + c1.w};
;             const int tok = t - NCTX;
;             const int q = (ropemode == 1) ? (cc & 3) : ((cc & 7) >> 1);
;             const int pos = (q < 2) ? (tok >> 6) : (tok & 63);
;             const float2* tab = (ropemode == 1) ? (T32 + pos * 8) : (T64 + pos * 16 + (cc & 1) * 8);
.LBB0_213:
	v_add_u32_e32 v122, 0x500, v204
	v_ashrrev_i32_e32 v124, 4, v122
	v_ashrrev_i32_e32 v122, 3, v122
	v_and_b32_e32 v122, 0xffffff80, v122
	v_and_b32_e32 v124, 63, v124
	v_add_u32_e32 v122, s28, v122
	v_or_b32_e32 v122, v122, v124
	v_mul_hi_i32 v124, v122, s55
	v_lshrrev_b32_e32 v160, 31, v124
	v_ashrrev_i32_e32 v124, 9, v124
	v_add_u32_e32 v124, v124, v160
	v_mul_i32_i24_e32 v124, 0x900, v124
	v_sub_u32_e32 v122, v122, v124
	v_add_u32_e32 v124, 0xffffff00, v122
	v_lshrrev_b32_e32 v124, 6, v124
	v_and_b32_e32 v122, 63, v122
	v_cndmask_b32_e64 v122, v122, v124, s[4:5]
	s_andn2_b64 vcc, exec, s[44:45]
	s_cbranch_vccnz .Lrp_b_0_4
	v_lshlrev_b32_e32 v160, 6, v122
	v_lshl_add_u64 v[120:121], s[18:19], 0, v[160:161]
	s_branch .Lrp_l_0_4

;   DI void operator()(int mt, int nt, int wm, int wn, int r, int h, f32x16 (&acc)[WM][2]) const {
;     ...
;             const float pr[8] = {p0.x + c0.x, p0.y + c0.y, p0.z + c0.z, p0.w + c0.w, p1.x + c1.x, p1.y + c1.y, p1.z + c1.z, p1.w + c1.w};
;             const int tok = t - NCTX;
;             const int q = (ropemode == 1) ? (cc & 3) : ((cc & 7) >> 1);
;             const int pos = (q < 2) ? (tok >> 6) : (tok & 63);
;             const float2* tab = (ropemode == 1) ? (T32 + pos * 8) : (T64 + pos * 16 + (cc & 1) * 8);
;             const float sgn = (q & 1) ? 1.f : -1.f;
; #pragma unroll
;             for (int k = 0; k < 8; ++k) { const float2 cs = tab[k]; v[k] = v[k] * cs.x + sgn * pr[k] * cs.y; }
.Lrp_l_0_4:
	global_load_dwordx4 v[112:115], v[120:121], off
	global_load_dwordx4 v[116:119], v[120:121], off offset:16
	global_load_dwordx4 v[214:217], v[120:121], off offset:32
	global_load_dwordx4 v[246:249], v[120:121], off offset:48
	s_waitcnt vmcnt(4) lgkmcnt(1)
	v_add_f32_e32 v80, v84, v213
	v_add_f32_e32 v81, v85, v218
	v_add_f32_e32 v84, v86, v219
	v_add_f32_e32 v85, v87, v245
	s_waitcnt lgkmcnt(0)
	v_add_f32_e32 v86, v76, v250
	v_add_f32_e32 v87, v77, v251
	v_add_f32_e32 v91, v78, v126
	v_add_f32_e32 v99, v79, v127
	v_mov_b32_e32 v72, v228
	v_mov_b32_e32 v73, v229
	v_mov_b32_e32 v74, v230
	v_mov_b32_e32 v75, v231
	v_mov_b32_e32 v79, v69
	v_cndmask_b32_e64 v78, v80, -v80, s[0:1]
	v_cndmask_b32_e64 v84, v84, -v84, s[0:1]
	v_cndmask_b32_e64 v86, v86, -v86, s[0:1]
	s_waitcnt vmcnt(4) lgkmcnt(0)
	v_mov_b32_e32 v76, v73
	v_cndmask_b32_e64 v73, v81, -v81, s[0:1]
	v_mov_b32_e32 v69, v73
	v_mov_b32_e32 v73, v75
	v_mov_b32_e32 v77, v74
	v_pk_mul_f32 v[80:81], v[68:69], v[72:73]
	v_mov_b32_e32 v72, v232
	v_mov_b32_e32 v73, v233
	v_mov_b32_e32 v74, v234
	v_mov_b32_e32 v75, v235
	v_cndmask_b32_e64 v68, v85, -v85, s[0:1]
	v_mov_b32_e32 v85, v71
	v_mov_b32_e32 v71, v68
	s_waitcnt vmcnt(4) lgkmcnt(0)
	v_mov_b32_e32 v82, v73
	v_mov_b32_e32 v73, v75
	v_pk_mul_f32 v[72:73], v[70:71], v[72:73]
	v_mov_b32_e32 v68, v236
	v_mov_b32_e32 v69, v237
	v_mov_b32_e32 v70, v238
	v_mov_b32_e32 v71, v239
	v_mov_b32_e32 v83, v74
	s_waitcnt vmcnt(4) lgkmcnt(0)
	v_mov_b32_e32 v74, v69
	v_cndmask_b32_e64 v69, v87, -v87, s[0:1]
	v_mov_b32_e32 v87, v65
	v_mov_b32_e32 v65, v69
	v_mov_b32_e32 v69, v71
	v_mov_b32_e32 v75, v70
	v_pk_mul_f32 v[64:65], v[64:65], v[68:69]
	v_mov_b32_e32 v68, v240
	v_mov_b32_e32 v69, v241
	v_mov_b32_e32 v70, v242
	v_mov_b32_e32 v71, v243
	v_pk_fma_f32 v[64:65], v[86:87], v[74:75], v[64:65]
	s_waitcnt vmcnt(4) lgkmcnt(0)
	v_mul_f32_e32 v66, v66, v68
	v_cndmask_b32_e64 v68, v91, -v91, s[0:1]
	v_mul_f32_e32 v92, v68, v69
	v_cndmask_b32_e64 v69, v99, -v99, s[0:1]
	v_mov_b32_e32 v68, v67
	v_pk_mul_f32 v[68:69], v[68:69], v[70:71]
	v_pk_fma_f32 v[70:71], v[84:85], v[82:83], v[72:73]
	v_mov_b32_e32 v67, v68
	v_mov_b32_e32 v93, v69
	v_pk_fma_f32 v[68:69], v[78:79], v[76:77], v[80:81]
	v_pk_add_f32 v[66:67], v[66:67], v[92:93]

;   DI void operator()(int mt, int nt, int wm, int wn, int r, int h, f32x16 (&acc)[WM][2]) const {
;     ...
;         const int id = tid + 256 * j;
;         const int lr = id >> 4, cc = id & 15;
;         const int row = mt * (WM * 64) + (lr >> 6) * (WM * 32) + ps * 64 + (lr & 63);
;         const int col0 = nt * 128 + cc * 8;
;         if (col0 < PW) {
;           const int t = row % NTOK;
;           const int ropemode = (t >= NCTX) ? ropemode0 : 0;
;           const float4 a0 = *(const float4*)(T + lr * LD + cc * 8), a1 = *(const float4*)(T + lr * LD + cc * 8 + 4);
;           const float4 b0 = *(const float4*)(bias + col0), b1 = *(const float4*)(bias + col0 + 4);
;           float v[8] = {a0.x + b0.x, a0.y + b0.y, a0.z + b0.z, a0.w + b0.w, a1.x + b1.x, a1.y + b1.y, a1.z + b1.z, a1.w + b1.w};
;           if (ropemode != 0) {
;             const int pc = (ropemode == 1) ? (cc ^ 1) : (cc ^ 2);
;             const float4 p0 = *(const float4*)(T + lr * LD + pc * 8), p1 = *(const float4*)(T + lr * LD + pc * 8 + 4);
;             const float4 c0 = *(const float4*)(bias + nt * 128 + pc * 8), c1 = *(const float4*)(bias + nt * 128 + pc * 8 + 4);
.LBB0_216:
	s_or_b64 exec, exec, s[8:9]
	s_nop 0
	v_add_u32_e32 v64, 0x500, v204
	v_ashrrev_i32_e32 v99, 4, v64
	v_ashrrev_i32_e32 v64, 3, v64
	v_and_b32_e32 v201, 0xffffff80, v64
	v_mul_lo_u32 v107, v99, s66
	v_add_u32_e32 v210, s28, v201
	v_and_b32_e32 v151, 63, v99
	v_lshl_add_u32 v170, v130, 2, v107
	s_and_saveexec_b64 s[8:9], s[6:7]
	s_cbranch_execz .LBB0_225
	v_or_b32_e32 v90, v210, v151
	v_mul_hi_i32 v80, v90, s55
	ds_read_b128 v[68:71], v170
	ds_read_b128 v[76:79], v170 offset:16
	v_lshrrev_b32_e32 v81, 31, v80
	v_ashrrev_i32_e32 v80, 9, v80
	v_add_u32_e32 v80, v80, v81
	v_mul_i32_i24_e32 v80, 0x900, v80
	v_sub_u32_e32 v91, v90, v80
	s_xor_b64 s[20:21], s[46:47], -1
	v_cmp_lt_i32_e32 vcc, s62, v91
	s_and_b64 s[26:27], vcc, s[20:21]
	s_waitcnt lgkmcnt(0)
	v_pk_add_f32 v[68:69], v[68:69], v[220:221]
	v_pk_add_f32 v[70:71], v[70:71], v[222:223]
	v_pk_add_f32 v[64:65], v[76:77], v[224:225]
	v_pk_add_f32 v[66:67], v[78:79], v[226:227]
	s_and_saveexec_b64 s[20:21], s[26:27]
	s_cbranch_execz .LBB0_223
	s_lshl_b64 s[26:27], s[24:25], 2
	s_add_u32 s26, s14, s26
	v_lshlrev_b32_e32 v76, 2, v132
	s_addc_u32 s27, s15, s27
	v_add_u32_e32 v76, v107, v76
	ds_read_b128 v[84:87], v76
	ds_read_b128 v[76:79], v76 offset:16
	v_add_u32_e32 v92, 0xffffff00, v91
	v_lshrrev_b32_e32 v92, 6, v92
	v_and_b32_e32 v91, 63, v91
	v_cndmask_b32_e64 v91, v91, v92, s[4:5]
	s_andn2_b64 vcc, exec, s[44:45]
	s_mov_b64 s[26:27], -1
	s_cbranch_vccnz .LBB0_220
	v_lshlrev_b32_e32 v160, 6, v91
	v_lshl_add_u64 v[92:93], s[18:19], 0, v[160:161]
	s_mov_b64 s[26:27], 0

;   DI void operator()(int mt, int nt, int wm, int wn, int r, int h, f32x16 (&acc)[WM][2]) const {
;     ...
;             const float pr[8] = {p0.x + c0.x, p0.y + c0.y, p0.z + c0.z, p0.w + c0.w, p1.x + c1.x, p1.y + c1.y, p1.z + c1.z, p1.w + c1.w};
;             const int tok = t - NCTX;
;             const int q = (ropemode == 1) ? (cc & 3) : ((cc & 7) >> 1);
;             const int pos = (q < 2) ? (tok >> 6) : (tok & 63);
;             const float2* tab = (ropemode == 1) ? (T32 + pos * 8) : (T64 + pos * 16 + (cc & 1) * 8);
.LBB0_222:
	v_add_u32_e32 v122, 0x600, v204
	v_ashrrev_i32_e32 v124, 4, v122
	v_ashrrev_i32_e32 v122, 3, v122
	v_and_b32_e32 v122, 0xffffff80, v122
	v_and_b32_e32 v124, 63, v124
	v_add_u32_e32 v122, s28, v122
	v_or_b32_e32 v122, v122, v124
	v_mul_hi_i32 v124, v122, s55
	v_lshrrev_b32_e32 v160, 31, v124
	v_ashrrev_i32_e32 v124, 9, v124
	v_add_u32_e32 v124, v124, v160
	v_mul_i32_i24_e32 v124, 0x900, v124
	v_sub_u32_e32 v122, v122, v124
	v_add_u32_e32 v124, 0xffffff00, v122
	v_lshrrev_b32_e32 v124, 6, v124
	v_and_b32_e32 v122, 63, v122
	v_cndmask_b32_e64 v122, v122, v124, s[4:5]
	s_andn2_b64 vcc, exec, s[44:45]
	s_cbranch_vccnz .Lrp_b_0_5
	v_lshlrev_b32_e32 v160, 6, v122
	v_lshl_add_u64 v[120:121], s[18:19], 0, v[160:161]
	s_branch .Lrp_l_0_5

;   DI void operator()(int mt, int nt, int wm, int wn, int r, int h, f32x16 (&acc)[WM][2]) const {
;     ...
;             const float pr[8] = {p0.x + c0.x, p0.y + c0.y, p0.z + c0.z, p0.w + c0.w, p1.x + c1.x, p1.y + c1.y, p1.z + c1.z, p1.w + c1.w};
;             const int tok = t - NCTX;
;             const int q = (ropemode == 1) ? (cc & 3) : ((cc & 7) >> 1);
;             const int pos = (q < 2) ? (tok >> 6) : (tok & 63);
;             const float2* tab = (ropemode == 1) ? (T32 + pos * 8) : (T64 + pos * 16 + (cc & 1) * 8);
;             const float sgn = (q & 1) ? 1.f : -1.f;
; #pragma unroll
;             for (int k = 0; k < 8; ++k) { const float2 cs = tab[k]; v[k] = v[k] * cs.x + sgn * pr[k] * cs.y; }
.Lrp_l_0_5:
	global_load_dwordx4 v[228:231], v[120:121], off
	global_load_dwordx4 v[232:235], v[120:121], off offset:16
	global_load_dwordx4 v[236:239], v[120:121], off offset:32
	global_load_dwordx4 v[240:243], v[120:121], off offset:48
	s_waitcnt vmcnt(4) lgkmcnt(1)
	v_add_f32_e32 v80, v84, v213
	v_add_f32_e32 v81, v85, v218
	v_add_f32_e32 v84, v86, v219
	v_add_f32_e32 v85, v87, v245
	s_waitcnt lgkmcnt(0)
	v_add_f32_e32 v86, v76, v250
	v_add_f32_e32 v87, v77, v251
	v_add_f32_e32 v91, v78, v126
	v_add_f32_e32 v100, v79, v127
	v_mov_b32_e32 v72, v112
	v_mov_b32_e32 v73, v113
	v_mov_b32_e32 v74, v114
	v_mov_b32_e32 v75, v115
	v_mov_b32_e32 v79, v69
	v_cndmask_b32_e64 v78, v80, -v80, s[0:1]
	v_cndmask_b32_e64 v84, v84, -v84, s[0:1]
	v_cndmask_b32_e64 v86, v86, -v86, s[0:1]
	s_waitcnt vmcnt(4) lgkmcnt(0)
	v_mov_b32_e32 v76, v73
	v_cndmask_b32_e64 v73, v81, -v81, s[0:1]
	v_mov_b32_e32 v69, v73
	v_mov_b32_e32 v73, v75
	v_mov_b32_e32 v77, v74
	v_pk_mul_f32 v[80:81], v[68:69], v[72:73]
	v_mov_b32_e32 v72, v116
	v_mov_b32_e32 v73, v117
	v_mov_b32_e32 v74, v118
	v_mov_b32_e32 v75, v119
	v_cndmask_b32_e64 v68, v85, -v85, s[0:1]
	v_mov_b32_e32 v85, v71
	v_mov_b32_e32 v71, v68
	s_waitcnt vmcnt(4) lgkmcnt(0)
	v_mov_b32_e32 v82, v73
	v_mov_b32_e32 v73, v75
	v_pk_mul_f32 v[72:73], v[70:71], v[72:73]
	v_mov_b32_e32 v68, v214
	v_mov_b32_e32 v69, v215
	v_mov_b32_e32 v70, v216
	v_mov_b32_e32 v71, v217
	v_mov_b32_e32 v83, v74
	s_waitcnt vmcnt(4) lgkmcnt(0)
	v_mov_b32_e32 v74, v69
	v_cndmask_b32_e64 v69, v87, -v87, s[0:1]
	v_mov_b32_e32 v87, v65
	v_mov_b32_e32 v65, v69
	v_mov_b32_e32 v69, v71
	v_mov_b32_e32 v75, v70
	v_pk_mul_f32 v[64:65], v[64:65], v[68:69]
	v_mov_b32_e32 v68, v246
	v_mov_b32_e32 v69, v247
	v_mov_b32_e32 v70, v248
	v_mov_b32_e32 v71, v249
	v_pk_fma_f32 v[64:65], v[86:87], v[74:75], v[64:65]
	s_waitcnt vmcnt(4) lgkmcnt(0)
	v_mul_f32_e32 v66, v66, v68
	v_cndmask_b32_e64 v68, v91, -v91, s[0:1]
	v_mul_f32_e32 v92, v68, v69
	v_cndmask_b32_e64 v69, v100, -v100, s[0:1]
	v_mov_b32_e32 v68, v67
	v_pk_mul_f32 v[68:69], v[68:69], v[70:71]
	v_pk_fma_f32 v[70:71], v[84:85], v[82:83], v[72:73]
	v_mov_b32_e32 v67, v68
	v_mov_b32_e32 v93, v69
	v_pk_fma_f32 v[68:69], v[78:79], v[76:77], v[80:81]
	v_pk_add_f32 v[66:67], v[66:67], v[92:93]

;   DI void operator()(int mt, int nt, int wm, int wn, int r, int h, f32x16 (&acc)[WM][2]) const {
;     ...
;         const int id = tid + 256 * j;
;         const int lr = id >> 4, cc = id & 15;
;         const int row = mt * (WM * 64) + (lr >> 6) * (WM * 32) + ps * 64 + (lr & 63);
;         const int col0 = nt * 128 + cc * 8;
;         if (col0 < PW) {
;           const int t = row % NTOK;
;           const int ropemode = (t >= NCTX) ? ropemode0 : 0;
;           const float4 a0 = *(const float4*)(T + lr * LD + cc * 8), a1 = *(const float4*)(T + lr * LD + cc * 8 + 4);
;           const float4 b0 = *(const float4*)(bias + col0), b1 = *(const float4*)(bias + col0 + 4);
;           float v[8] = {a0.x + b0.x, a0.y + b0.y, a0.z + b0.z, a0.w + b0.w, a1.x + b1.x, a1.y + b1.y, a1.z + b1.z, a1.w + b1.w};
;           if (ropemode != 0) {
;             const int pc = (ropemode == 1) ? (cc ^ 1) : (cc ^ 2);
;             const float4 p0 = *(const float4*)(T + lr * LD + pc * 8), p1 = *(const float4*)(T + lr * LD + pc * 8 + 4);
;             const float4 c0 = *(const float4*)(bias + nt * 128 + pc * 8), c1 = *(const float4*)(bias + nt * 128 + pc * 8 + 4);
.LBB0_225:
	s_or_b64 exec, exec, s[8:9]
	s_nop 0
	v_add_u32_e32 v64, 0x600, v204
	v_ashrrev_i32_e32 v100, 4, v64
	v_ashrrev_i32_e32 v64, 3, v64
	v_and_b32_e32 v202, 0xffffff80, v64
	v_mul_lo_u32 v108, v100, s66
	v_add_u32_e32 v211, s28, v202
	v_and_b32_e32 v196, 63, v100
	v_lshl_add_u32 v197, v130, 2, v108
	s_and_saveexec_b64 s[8:9], s[6:7]
	s_cbranch_execz .LBB0_234
	v_or_b32_e32 v90, v211, v196
	v_mul_hi_i32 v80, v90, s55
	ds_read_b128 v[68:71], v197
	ds_read_b128 v[76:79], v197 offset:16
	v_lshrrev_b32_e32 v81, 31, v80
	v_ashrrev_i32_e32 v80, 9, v80
	v_add_u32_e32 v80, v80, v81
	v_mul_i32_i24_e32 v80, 0x900, v80
	v_sub_u32_e32 v91, v90, v80
	s_xor_b64 s[20:21], s[46:47], -1
	v_cmp_lt_i32_e32 vcc, s62, v91
	s_and_b64 s[26:27], vcc, s[20:21]
	s_waitcnt lgkmcnt(0)
	v_pk_add_f32 v[68:69], v[68:69], v[220:221]
	v_pk_add_f32 v[70:71], v[70:71], v[222:223]
	v_pk_add_f32 v[64:65], v[76:77], v[224:225]
	v_pk_add_f32 v[66:67], v[78:79], v[226:227]
	s_and_saveexec_b64 s[20:21], s[26:27]
	s_cbranch_execz .LBB0_232
	s_lshl_b64 s[26:27], s[24:25], 2
	s_add_u32 s26, s14, s26
	v_lshlrev_b32_e32 v76, 2, v132
	s_addc_u32 s27, s15, s27
	v_add_u32_e32 v76, v108, v76
	ds_read_b128 v[84:87], v76
	ds_read_b128 v[76:79], v76 offset:16
	v_add_u32_e32 v92, 0xffffff00, v91
	v_lshrrev_b32_e32 v92, 6, v92
	v_and_b32_e32 v91, 63, v91
	v_cndmask_b32_e64 v91, v91, v92, s[4:5]
	s_andn2_b64 vcc, exec, s[44:45]
	s_mov_b64 s[26:27], -1
	s_cbranch_vccnz .LBB0_229
	v_lshlrev_b32_e32 v160, 6, v91
	v_lshl_add_u64 v[92:93], s[18:19], 0, v[160:161]
	s_mov_b64 s[26:27], 0

;   DI void operator()(int mt, int nt, int wm, int wn, int r, int h, f32x16 (&acc)[WM][2]) const {
;     ...
;             const float pr[8] = {p0.x + c0.x, p0.y + c0.y, p0.z + c0.z, p0.w + c0.w, p1.x + c1.x, p1.y + c1.y, p1.z + c1.z, p1.w + c1.w};
;             const int tok = t - NCTX;
;             const int q = (ropemode == 1) ? (cc & 3) : ((cc & 7) >> 1);
;             const int pos = (q < 2) ? (tok >> 6) : (tok & 63);
;             const float2* tab = (ropemode == 1) ? (T32 + pos * 8) : (T64 + pos * 16 + (cc & 1) * 8);
.LBB0_231:
	v_add_u32_e32 v122, 0x700, v204
	v_ashrrev_i32_e32 v124, 4, v122
	v_ashrrev_i32_e32 v122, 3, v122
	v_and_b32_e32 v122, 0xffffff80, v122
	v_and_b32_e32 v124, 63, v124
	v_add_u32_e32 v122, s28, v122
	v_or_b32_e32 v122, v122, v124
	v_mul_hi_i32 v124, v122, s55
	v_lshrrev_b32_e32 v160, 31, v124
	v_ashrrev_i32_e32 v124, 9, v124
	v_add_u32_e32 v124, v124, v160
	v_mul_i32_i24_e32 v124, 0x900, v124
	v_sub_u32_e32 v122, v122, v124
	v_add_u32_e32 v124, 0xffffff00, v122
	v_lshrrev_b32_e32 v124, 6, v124
	v_and_b32_e32 v122, 63, v122
	v_cndmask_b32_e64 v122, v122, v124, s[4:5]
	s_andn2_b64 vcc, exec, s[44:45]
	s_cbranch_vccnz .Lrp_b_0_6
	v_lshlrev_b32_e32 v160, 6, v122
	v_lshl_add_u64 v[120:121], s[18:19], 0, v[160:161]
	s_branch .Lrp_l_0_6

;   DI void operator()(int mt, int nt, int wm, int wn, int r, int h, f32x16 (&acc)[WM][2]) const {
;     ...
;             const float pr[8] = {p0.x + c0.x, p0.y + c0.y, p0.z + c0.z, p0.w + c0.w, p1.x + c1.x, p1.y + c1.y, p1.z + c1.z, p1.w + c1.w};
;             const int tok = t - NCTX;
;             const int q = (ropemode == 1) ? (cc & 3) : ((cc & 7) >> 1);
;             const int pos = (q < 2) ? (tok >> 6) : (tok & 63);
;             const float2* tab = (ropemode == 1) ? (T32 + pos * 8) : (T64 + pos * 16 + (cc & 1) * 8);
;             const float sgn = (q & 1) ? 1.f : -1.f;
; #pragma unroll
;             for (int k = 0; k < 8; ++k) { const float2 cs = tab[k]; v[k] = v[k] * cs.x + sgn * pr[k] * cs.y; }
.Lrp_l_0_6:
	global_load_dwordx4 v[112:115], v[120:121], off
	global_load_dwordx4 v[116:119], v[120:121], off offset:16
	global_load_dwordx4 v[214:217], v[120:121], off offset:32
	global_load_dwordx4 v[246:249], v[120:121], off offset:48
	s_waitcnt vmcnt(4) lgkmcnt(1)
	v_add_f32_e32 v80, v84, v213
	v_add_f32_e32 v81, v85, v218
	v_add_f32_e32 v84, v86, v219
	v_add_f32_e32 v85, v87, v245
	s_waitcnt lgkmcnt(0)
	v_add_f32_e32 v86, v76, v250
	v_add_f32_e32 v87, v77, v251
	v_add_f32_e32 v91, v78, v126
	v_add_f32_e32 v101, v79, v127
	v_mov_b32_e32 v72, v228
	v_mov_b32_e32 v73, v229
	v_mov_b32_e32 v74, v230
	v_mov_b32_e32 v75, v231
	v_mov_b32_e32 v79, v69
	v_cndmask_b32_e64 v78, v80, -v80, s[0:1]
	v_cndmask_b32_e64 v84, v84, -v84, s[0:1]
	v_cndmask_b32_e64 v86, v86, -v86, s[0:1]
	s_waitcnt vmcnt(4) lgkmcnt(0)
	v_mov_b32_e32 v76, v73
	v_cndmask_b32_e64 v73, v81, -v81, s[0:1]
	v_mov_b32_e32 v69, v73
	v_mov_b32_e32 v73, v75
	v_mov_b32_e32 v77, v74
	v_pk_mul_f32 v[80:81], v[68:69], v[72:73]
	v_mov_b32_e32 v72, v232
	v_mov_b32_e32 v73, v233
	v_mov_b32_e32 v74, v234
	v_mov_b32_e32 v75, v235
	v_cndmask_b32_e64 v68, v85, -v85, s[0:1]
	v_mov_b32_e32 v85, v71
	v_mov_b32_e32 v71, v68
	s_waitcnt vmcnt(4) lgkmcnt(0)
	v_mov_b32_e32 v82, v73
	v_mov_b32_e32 v73, v75
	v_pk_mul_f32 v[72:73], v[70:71], v[72:73]
	v_mov_b32_e32 v68, v236
	v_mov_b32_e32 v69, v237
	v_mov_b32_e32 v70, v238
	v_mov_b32_e32 v71, v239
	v_mov_b32_e32 v83, v74
	s_waitcnt vmcnt(4) lgkmcnt(0)
	v_mov_b32_e32 v74, v69
	v_cndmask_b32_e64 v69, v87, -v87, s[0:1]
	v_mov_b32_e32 v87, v65
	v_mov_b32_e32 v65, v69
	v_mov_b32_e32 v69, v71
	v_mov_b32_e32 v75, v70
	v_pk_mul_f32 v[64:65], v[64:65], v[68:69]
	v_mov_b32_e32 v68, v240
	v_mov_b32_e32 v69, v241
	v_mov_b32_e32 v70, v242
	v_mov_b32_e32 v71, v243
	v_pk_fma_f32 v[64:65], v[86:87], v[74:75], v[64:65]
	s_waitcnt vmcnt(4) lgkmcnt(0)
	v_mul_f32_e32 v66, v66, v68
	v_cndmask_b32_e64 v68, v91, -v91, s[0:1]
	v_mul_f32_e32 v92, v68, v69
	v_cndmask_b32_e64 v69, v101, -v101, s[0:1]
	v_mov_b32_e32 v68, v67
	v_pk_mul_f32 v[68:69], v[68:69], v[70:71]
	v_pk_fma_f32 v[70:71], v[84:85], v[82:83], v[72:73]
	v_mov_b32_e32 v67, v68
	v_mov_b32_e32 v93, v69
	v_pk_fma_f32 v[68:69], v[78:79], v[76:77], v[80:81]
	v_pk_add_f32 v[66:67], v[66:67], v[92:93]

;   DI void operator()(int mt, int nt, int wm, int wn, int r, int h, f32x16 (&acc)[WM][2]) const {
;     ...
;         const int id = tid + 256 * j;
;         const int lr = id >> 4, cc = id & 15;
;         const int row = mt * (WM * 64) + (lr >> 6) * (WM * 32) + ps * 64 + (lr & 63);
;         const int col0 = nt * 128 + cc * 8;
;         if (col0 < PW) {
;           const int t = row % NTOK;
;           const int ropemode = (t >= NCTX) ? ropemode0 : 0;
;           const float4 a0 = *(const float4*)(T + lr * LD + cc * 8), a1 = *(const float4*)(T + lr * LD + cc * 8 + 4);
;           const float4 b0 = *(const float4*)(bias + col0), b1 = *(const float4*)(bias + col0 + 4);
;           float v[8] = {a0.x + b0.x, a0.y + b0.y, a0.z + b0.z, a0.w + b0.w, a1.x + b1.x, a1.y + b1.y, a1.z + b1.z, a1.w + b1.w};
;           if (ropemode != 0) {
;             const int pc = (ropemode == 1) ? (cc ^ 1) : (cc ^ 2);
;             const float4 p0 = *(const float4*)(T + lr * LD + pc * 8), p1 = *(const float4*)(T + lr * LD + pc * 8 + 4);
;             const float4 c0 = *(const float4*)(bias + nt * 128 + pc * 8), c1 = *(const float4*)(bias + nt * 128 + pc * 8 + 4);
.LBB0_234:
	s_or_b64 exec, exec, s[8:9]
	s_nop 0
	v_add_u32_e32 v64, 0x700, v204
	v_ashrrev_i32_e32 v101, 4, v64
	v_ashrrev_i32_e32 v64, 3, v64
	v_and_b32_e32 v203, 0xffffff80, v64
	v_mul_lo_u32 v109, v101, s66
	v_add_u32_e32 v212, s28, v203
	v_and_b32_e32 v199, 63, v101
	v_lshl_add_u32 v200, v130, 2, v109
	s_and_saveexec_b64 s[8:9], s[6:7]
	s_cbranch_execz .LBB0_243
	v_or_b32_e32 v90, v212, v199
	v_mul_hi_i32 v80, v90, s55
	ds_read_b128 v[68:71], v200
	ds_read_b128 v[76:79], v200 offset:16
	v_lshrrev_b32_e32 v81, 31, v80
	v_ashrrev_i32_e32 v80, 9, v80
	v_add_u32_e32 v80, v80, v81
	v_mul_i32_i24_e32 v80, 0x900, v80
	v_sub_u32_e32 v91, v90, v80
	s_xor_b64 s[20:21], s[46:47], -1
	v_cmp_lt_i32_e32 vcc, s62, v91
	s_and_b64 s[26:27], vcc, s[20:21]
	s_waitcnt lgkmcnt(0)
	v_pk_add_f32 v[68:69], v[68:69], v[220:221]
	v_pk_add_f32 v[70:71], v[70:71], v[222:223]
	v_pk_add_f32 v[64:65], v[76:77], v[224:225]
	v_pk_add_f32 v[66:67], v[78:79], v[226:227]
	s_and_saveexec_b64 s[20:21], s[26:27]
	s_cbranch_execz .LBB0_241
	s_lshl_b64 s[26:27], s[24:25], 2
	s_add_u32 s26, s14, s26
	v_lshlrev_b32_e32 v76, 2, v132
	s_addc_u32 s27, s15, s27
	v_add_u32_e32 v76, v109, v76
	ds_read_b128 v[84:87], v76
	ds_read_b128 v[76:79], v76 offset:16
	v_add_u32_e32 v92, 0xffffff00, v91
	v_lshrrev_b32_e32 v92, 6, v92
	v_and_b32_e32 v91, 63, v91
	v_cndmask_b32_e64 v91, v91, v92, s[4:5]
	s_andn2_b64 vcc, exec, s[44:45]
	s_mov_b64 s[26:27], -1
	s_cbranch_vccnz .LBB0_238
	v_lshlrev_b32_e32 v160, 6, v91
	v_lshl_add_u64 v[92:93], s[18:19], 0, v[160:161]
	s_mov_b64 s[26:27], 0

;   DI void operator()(int mt, int nt, int wm, int wn, int r, int h, f32x16 (&acc)[WM][2]) const {
;     ...
;           if (ropemode != 0) {
;             const int pc = (ropemode == 1) ? (cc ^ 1) : (cc ^ 2);
;             const float4 p0 = *(const float4*)(T + lr * LD + pc * 8), p1 = *(const float4*)(T + lr * LD + pc * 8 + 4);
;             const float4 c0 = *(const float4*)(bias + nt * 128 + pc * 8), c1 = *(const float4*)(bias + nt * 128 + pc * 8 + 4);
;             const float pr[8] = {p0.x + c0.x, p0.y + c0.y, p0.z + c0.z, p0.w + c0.w, p1.x + c1.x, p1.y + c1.y, p1.z + c1.z, p1.w + c1.w};
;             const int tok = t - NCTX;
;             const int q = (ropemode == 1) ? (cc & 3) : ((cc & 7) >> 1);
;             const int pos = (q < 2) ? (tok >> 6) : (tok & 63);
;             const float2* tab = (ropemode == 1) ? (T32 + pos * 8) : (T64 + pos * 16 + (cc & 1) * 8);
;             const float sgn = (q & 1) ? 1.f : -1.f;
; #pragma unroll
;             for (int k = 0; k < 8; ++k) { const float2 cs = tab[k]; v[k] = v[k] * cs.x + sgn * pr[k] * cs.y; }
.LBB0_240:
	s_waitcnt vmcnt(0) lgkmcnt(1)
	v_add_f32_e32 v80, v84, v213
	v_add_f32_e32 v81, v85, v218
	v_add_f32_e32 v84, v86, v219
	v_add_f32_e32 v85, v87, v245
	s_waitcnt lgkmcnt(0)
	v_add_f32_e32 v86, v76, v250
	v_add_f32_e32 v87, v77, v251
	v_add_f32_e32 v91, v78, v126
	v_add_f32_e32 v160, v79, v127
	v_mov_b32_e32 v72, v112
	v_mov_b32_e32 v73, v113
	v_mov_b32_e32 v74, v114
	v_mov_b32_e32 v75, v115
	v_mov_b32_e32 v79, v69
	v_cndmask_b32_e64 v78, v80, -v80, s[0:1]
	v_cndmask_b32_e64 v84, v84, -v84, s[0:1]
	v_cndmask_b32_e64 v86, v86, -v86, s[0:1]
	s_waitcnt vmcnt(0) lgkmcnt(0)
	v_mov_b32_e32 v76, v73
	v_cndmask_b32_e64 v73, v81, -v81, s[0:1]
	v_mov_b32_e32 v69, v73
	v_mov_b32_e32 v73, v75
	v_mov_b32_e32 v77, v74
	v_pk_mul_f32 v[80:81], v[68:69], v[72:73]
	v_mov_b32_e32 v72, v116
	v_mov_b32_e32 v73, v117
	v_mov_b32_e32 v74, v118
	v_mov_b32_e32 v75, v119
	v_cndmask_b32_e64 v68, v85, -v85, s[0:1]
	v_mov_b32_e32 v85, v71
	v_mov_b32_e32 v71, v68
	s_waitcnt vmcnt(0) lgkmcnt(0)
	v_mov_b32_e32 v82, v73
	v_mov_b32_e32 v73, v75
	v_pk_mul_f32 v[72:73], v[70:71], v[72:73]
	v_mov_b32_e32 v68, v214
	v_mov_b32_e32 v69, v215
	v_mov_b32_e32 v70, v216
	v_mov_b32_e32 v71, v217
	v_mov_b32_e32 v83, v74
	s_waitcnt vmcnt(0) lgkmcnt(0)
	v_mov_b32_e32 v74, v69
	v_cndmask_b32_e64 v69, v87, -v87, s[0:1]
	v_mov_b32_e32 v87, v65
	v_mov_b32_e32 v65, v69
	v_mov_b32_e32 v69, v71
	v_mov_b32_e32 v75, v70
	v_pk_mul_f32 v[64:65], v[64:65], v[68:69]
	v_mov_b32_e32 v68, v246
	v_mov_b32_e32 v69, v247
	v_mov_b32_e32 v70, v248
	v_mov_b32_e32 v71, v249
	v_pk_fma_f32 v[64:65], v[86:87], v[74:75], v[64:65]
	s_waitcnt vmcnt(0) lgkmcnt(0)
	v_mul_f32_e32 v66, v66, v68
	v_cndmask_b32_e64 v68, v91, -v91, s[0:1]
	v_mul_f32_e32 v92, v68, v69
	v_cndmask_b32_e64 v69, v160, -v160, s[0:1]
	v_mov_b32_e32 v68, v67
	v_pk_mul_f32 v[68:69], v[68:69], v[70:71]
	v_pk_fma_f32 v[70:71], v[84:85], v[82:83], v[72:73]
	v_mov_b32_e32 v67, v68
	v_mov_b32_e32 v93, v69
	v_pk_fma_f32 v[68:69], v[78:79], v[76:77], v[80:81]
	v_pk_add_f32 v[66:67], v[66:67], v[92:93]

;   DI void operator()(int mt, int nt, int wm, int wn, int r, int h, f32x16 (&acc)[WM][2]) const {
;     ...
;             const float pr[8] = {p0.x + c0.x, p0.y + c0.y, p0.z + c0.z, p0.w + c0.w, p1.x + c1.x, p1.y + c1.y, p1.z + c1.z, p1.w + c1.w};
;             const int tok = t - NCTX;
;             const int q = (ropemode == 1) ? (cc & 3) : ((cc & 7) >> 1);
;             const int pos = (q < 2) ? (tok >> 6) : (tok & 63);
;             const float2* tab = (ropemode == 1) ? (T32 + pos * 8) : (T64 + pos * 16 + (cc & 1) * 8);
.LBB0_287:
	global_load_dwordx4 v[228:231], v[26:27], off
	global_load_dwordx4 v[232:235], v[26:27], off offset:16
	global_load_dwordx4 v[236:239], v[26:27], off offset:32
	global_load_dwordx4 v[240:243], v[26:27], off offset:48
	v_add_u32_e32 v122, 0x100, v204
	v_ashrrev_i32_e32 v124, 4, v122
	v_ashrrev_i32_e32 v122, 3, v122
	v_and_b32_e32 v122, 0xffffff80, v122
	v_and_b32_e32 v124, 63, v124
	v_add_u32_e32 v122, s43, v122
	v_or_b32_e32 v122, v122, v124
	v_mul_hi_i32 v124, v122, s55
	v_lshrrev_b32_e32 v160, 31, v124
	v_ashrrev_i32_e32 v124, 9, v124
	v_add_u32_e32 v124, v124, v160
	v_mul_i32_i24_e32 v124, 0x900, v124
	v_sub_u32_e32 v122, v122, v124
	v_add_u32_e32 v124, 0xffffff00, v122
	v_lshrrev_b32_e32 v124, 6, v124
	v_and_b32_e32 v122, 63, v122
	v_cndmask_b32_e64 v122, v122, v124, s[4:5]
	s_andn2_b64 vcc, exec, s[44:45]
	s_cbranch_vccnz .Lrp_b_1_0
	v_lshlrev_b32_e32 v160, 6, v122
	v_lshl_add_u64 v[120:121], s[18:19], 0, v[160:161]
	s_branch .Lrp_l_1_0

;   DI void operator()(int mt, int nt, int wm, int wn, int r, int h, f32x16 (&acc)[WM][2]) const {
;     ...
;             const float pr[8] = {p0.x + c0.x, p0.y + c0.y, p0.z + c0.z, p0.w + c0.w, p1.x + c1.x, p1.y + c1.y, p1.z + c1.z, p1.w + c1.w};
;             const int tok = t - NCTX;
;             const int q = (ropemode == 1) ? (cc & 3) : ((cc & 7) >> 1);
;             const int pos = (q < 2) ? (tok >> 6) : (tok & 63);
;             const float2* tab = (ropemode == 1) ? (T32 + pos * 8) : (T64 + pos * 16 + (cc & 1) * 8);
;             const float sgn = (q & 1) ? 1.f : -1.f;
; #pragma unroll
;             for (int k = 0; k < 8; ++k) { const float2 cs = tab[k]; v[k] = v[k] * cs.x + sgn * pr[k] * cs.y; }
.Lrp_l_1_0:
	global_load_dwordx4 v[112:115], v[120:121], off
	global_load_dwordx4 v[116:119], v[120:121], off offset:16
	global_load_dwordx4 v[214:217], v[120:121], off offset:32
	global_load_dwordx4 v[246:249], v[120:121], off offset:48
	s_waitcnt vmcnt(4) lgkmcnt(1)
	v_mov_b32_e32 v213, v16
	v_mov_b32_e32 v218, v17
	v_mov_b32_e32 v219, v18
	v_mov_b32_e32 v245, v19
	v_mov_b32_e32 v250, v8
	v_mov_b32_e32 v251, v9
	v_mov_b32_e32 v126, v10
	v_mov_b32_e32 v127, v11
	v_add_f32_e32 v16, v20, v16
	v_add_f32_e32 v17, v21, v17
	v_add_f32_e32 v20, v22, v18
	v_add_f32_e32 v21, v23, v19
	s_waitcnt lgkmcnt(0)
	v_add_f32_e32 v22, v12, v8
	v_add_f32_e32 v23, v13, v9
	v_add_f32_e32 v25, v14, v10
	v_add_f32_e32 v29, v15, v11
	v_mov_b32_e32 v8, v228
	v_mov_b32_e32 v9, v229
	v_mov_b32_e32 v10, v230
	v_mov_b32_e32 v11, v231
	v_mov_b32_e32 v15, v5
	v_cndmask_b32_e64 v14, v16, -v16, s[0:1]
	v_cndmask_b32_e64 v20, v20, -v20, s[0:1]
	v_cndmask_b32_e64 v22, v22, -v22, s[0:1]
	s_waitcnt vmcnt(4) lgkmcnt(0)
	v_mov_b32_e32 v12, v9
	v_cndmask_b32_e64 v9, v17, -v17, s[0:1]
	v_mov_b32_e32 v5, v9
	v_mov_b32_e32 v9, v11
	v_mov_b32_e32 v13, v10
	v_pk_mul_f32 v[16:17], v[4:5], v[8:9]
	v_mov_b32_e32 v8, v232
	v_mov_b32_e32 v9, v233
	v_mov_b32_e32 v10, v234
	v_mov_b32_e32 v11, v235
	v_cndmask_b32_e64 v4, v21, -v21, s[0:1]
	v_mov_b32_e32 v21, v7
	v_mov_b32_e32 v7, v4
	s_waitcnt vmcnt(4) lgkmcnt(0)
	v_mov_b32_e32 v18, v9
	v_mov_b32_e32 v9, v11
	v_pk_mul_f32 v[8:9], v[6:7], v[8:9]
	v_mov_b32_e32 v4, v236
	v_mov_b32_e32 v5, v237
	v_mov_b32_e32 v6, v238
	v_mov_b32_e32 v7, v239
	v_mov_b32_e32 v19, v10
	s_waitcnt vmcnt(4) lgkmcnt(0)
	v_mov_b32_e32 v10, v5
	v_cndmask_b32_e64 v5, v23, -v23, s[0:1]
	v_mov_b32_e32 v23, v1
	v_mov_b32_e32 v1, v5
	v_mov_b32_e32 v5, v7
	v_mov_b32_e32 v11, v6
	v_pk_mul_f32 v[0:1], v[0:1], v[4:5]
	v_mov_b32_e32 v4, v240
	v_mov_b32_e32 v5, v241
	v_mov_b32_e32 v6, v242
	v_mov_b32_e32 v7, v243
	v_pk_fma_f32 v[0:1], v[22:23], v[10:11], v[0:1]
	s_waitcnt vmcnt(4) lgkmcnt(0)
	v_mul_f32_e32 v2, v2, v4
	v_cndmask_b32_e64 v4, v25, -v25, s[0:1]
	v_mul_f32_e32 v26, v4, v5
	v_cndmask_b32_e64 v5, v29, -v29, s[0:1]
	v_mov_b32_e32 v4, v3
	v_pk_mul_f32 v[4:5], v[4:5], v[6:7]
	v_pk_fma_f32 v[6:7], v[20:21], v[18:19], v[8:9]
	v_mov_b32_e32 v3, v4
	v_mov_b32_e32 v27, v5
	v_pk_fma_f32 v[4:5], v[14:15], v[12:13], v[16:17]
	v_pk_add_f32 v[2:3], v[2:3], v[26:27]

;   DI void operator()(int mt, int nt, int wm, int wn, int r, int h, f32x16 (&acc)[WM][2]) const {
;     ...
;         const int id = tid + 256 * j;
;         const int lr = id >> 4, cc = id & 15;
;         const int row = mt * (WM * 64) + (lr >> 6) * (WM * 32) + ps * 64 + (lr & 63);
;         const int col0 = nt * 128 + cc * 8;
;         if (col0 < PW) {
;           const int t = row % NTOK;
;           const int ropemode = (t >= NCTX) ? ropemode0 : 0;
;           const float4 a0 = *(const float4*)(T + lr * LD + cc * 8), a1 = *(const float4*)(T + lr * LD + cc * 8 + 4);
;           const float4 b0 = *(const float4*)(bias + col0), b1 = *(const float4*)(bias + col0 + 4);
;           float v[8] = {a0.x + b0.x, a0.y + b0.y, a0.z + b0.z, a0.w + b0.w, a1.x + b1.x, a1.y + b1.y, a1.z + b1.z, a1.w + b1.w};
;           if (ropemode != 0) {
;             const int pc = (ropemode == 1) ? (cc ^ 1) : (cc ^ 2);
;             const float4 p0 = *(const float4*)(T + lr * LD + pc * 8), p1 = *(const float4*)(T + lr * LD + pc * 8 + 4);
;             const float4 c0 = *(const float4*)(bias + nt * 128 + pc * 8), c1 = *(const float4*)(bias + nt * 128 + pc * 8 + 4);
.LBB0_290:
	s_or_b64 exec, exec, s[8:9]
	v_add_u32_e32 v29, s43, v147
	s_and_saveexec_b64 s[8:9], s[6:7]
	s_cbranch_execz .LBB0_299
	v_or_b32_e32 v24, v29, v123
	v_mul_hi_i32 v16, v24, s55
	ds_read_b128 v[4:7], v125
	ds_read_b128 v[12:15], v125 offset:16
	v_lshrrev_b32_e32 v17, 31, v16
	v_ashrrev_i32_e32 v16, 9, v16
	v_add_u32_e32 v16, v16, v17
	v_mul_i32_i24_e32 v16, 0x900, v16
	v_sub_u32_e32 v25, v24, v16
	s_xor_b64 s[26:27], s[46:47], -1
	v_cmp_lt_i32_e32 vcc, s62, v25
	s_and_b64 s[28:29], vcc, s[26:27]
	s_waitcnt lgkmcnt(0)
	v_pk_add_f32 v[4:5], v[4:5], v[220:221]
	v_pk_add_f32 v[6:7], v[6:7], v[222:223]
	v_pk_add_f32 v[0:1], v[12:13], v[224:225]
	v_pk_add_f32 v[2:3], v[14:15], v[226:227]
	s_and_saveexec_b64 s[26:27], s[28:29]
	s_cbranch_execz .LBB0_297
	s_lshl_b64 s[28:29], s[24:25], 2
	s_add_u32 s28, s14, s28
	v_lshlrev_b32_e32 v12, 2, v132
	s_addc_u32 s29, s15, s29
	v_add_u32_e32 v12, v103, v12
	ds_read_b128 v[20:23], v12
	ds_read_b128 v[12:15], v12 offset:16
	v_add_u32_e32 v26, 0xffffff00, v25
	v_lshrrev_b32_e32 v26, 6, v26
	v_and_b32_e32 v25, 63, v25
	v_cndmask_b32_e64 v25, v25, v26, s[4:5]
	s_andn2_b64 vcc, exec, s[44:45]
	s_mov_b64 s[28:29], -1
	s_cbranch_vccnz .LBB0_294
	v_lshlrev_b32_e32 v160, 6, v25
	v_lshl_add_u64 v[26:27], s[18:19], 0, v[160:161]
	s_mov_b64 s[28:29], 0

;   DI void operator()(int mt, int nt, int wm, int wn, int r, int h, f32x16 (&acc)[WM][2]) const {
;     ...
;             const float pr[8] = {p0.x + c0.x, p0.y + c0.y, p0.z + c0.z, p0.w + c0.w, p1.x + c1.x, p1.y + c1.y, p1.z + c1.z, p1.w + c1.w};
;             const int tok = t - NCTX;
;             const int q = (ropemode == 1) ? (cc & 3) : ((cc & 7) >> 1);
;             const int pos = (q < 2) ? (tok >> 6) : (tok & 63);
;             const float2* tab = (ropemode == 1) ? (T32 + pos * 8) : (T64 + pos * 16 + (cc & 1) * 8);
.LBB0_296:
	v_add_u32_e32 v122, 0x200, v204
	v_ashrrev_i32_e32 v124, 4, v122
	v_ashrrev_i32_e32 v122, 3, v122
	v_and_b32_e32 v122, 0xffffff80, v122
	v_and_b32_e32 v124, 63, v124
	v_add_u32_e32 v122, s43, v122
	v_or_b32_e32 v122, v122, v124
	v_mul_hi_i32 v124, v122, s55
	v_lshrrev_b32_e32 v160, 31, v124
	v_ashrrev_i32_e32 v124, 9, v124
	v_add_u32_e32 v124, v124, v160
	v_mul_i32_i24_e32 v124, 0x900, v124
	v_sub_u32_e32 v122, v122, v124
	v_add_u32_e32 v124, 0xffffff00, v122
	v_lshrrev_b32_e32 v124, 6, v124
	v_and_b32_e32 v122, 63, v122
	v_cndmask_b32_e64 v122, v122, v124, s[4:5]
	s_andn2_b64 vcc, exec, s[44:45]
	s_cbranch_vccnz .Lrp_b_1_1
	v_lshlrev_b32_e32 v160, 6, v122
	v_lshl_add_u64 v[120:121], s[18:19], 0, v[160:161]
	s_branch .Lrp_l_1_1

;   DI void operator()(int mt, int nt, int wm, int wn, int r, int h, f32x16 (&acc)[WM][2]) const {
;     ...
;           if (ropemode != 0) {
;             const int pc = (ropemode == 1) ? (cc ^ 1) : (cc ^ 2);
;             const float4 p0 = *(const float4*)(T + lr * LD + pc * 8), p1 = *(const float4*)(T + lr * LD + pc * 8 + 4);
;             const float4 c0 = *(const float4*)(bias + nt * 128 + pc * 8), c1 = *(const float4*)(bias + nt * 128 + pc * 8 + 4);
;             const float pr[8] = {p0.x + c0.x, p0.y + c0.y, p0.z + c0.z, p0.w + c0.w, p1.x + c1.x, p1.y + c1.y, p1.z + c1.z, p1.w + c1.w};
;             const int tok = t - NCTX;
;             const int q = (ropemode == 1) ? (cc & 3) : ((cc & 7) >> 1);
;             const int pos = (q < 2) ? (tok >> 6) : (tok & 63);
;             const float2* tab = (ropemode == 1) ? (T32 + pos * 8) : (T64 + pos * 16 + (cc & 1) * 8);
;             const float sgn = (q & 1) ? 1.f : -1.f;
; #pragma unroll
;             for (int k = 0; k < 8; ++k) { const float2 cs = tab[k]; v[k] = v[k] * cs.x + sgn * pr[k] * cs.y; }
.Lrp_l_1_1:
	global_load_dwordx4 v[228:231], v[120:121], off
	global_load_dwordx4 v[232:235], v[120:121], off offset:16
	global_load_dwordx4 v[236:239], v[120:121], off offset:32
	global_load_dwordx4 v[240:243], v[120:121], off offset:48
	s_waitcnt vmcnt(4) lgkmcnt(1)
	v_add_f32_e32 v16, v20, v213
	v_add_f32_e32 v17, v21, v218
	v_add_f32_e32 v20, v22, v219
	v_add_f32_e32 v21, v23, v245
	s_waitcnt lgkmcnt(0)
	v_add_f32_e32 v22, v12, v250
	v_add_f32_e32 v23, v13, v251
	v_add_f32_e32 v25, v14, v126
	v_add_f32_e32 v30, v15, v127
	v_mov_b32_e32 v8, v112
	v_mov_b32_e32 v9, v113
	v_mov_b32_e32 v10, v114
	v_mov_b32_e32 v11, v115
	v_mov_b32_e32 v15, v5
	v_cndmask_b32_e64 v14, v16, -v16, s[0:1]
	v_cndmask_b32_e64 v20, v20, -v20, s[0:1]
	v_cndmask_b32_e64 v22, v22, -v22, s[0:1]
	s_waitcnt vmcnt(4) lgkmcnt(0)
	v_mov_b32_e32 v12, v9
	v_cndmask_b32_e64 v9, v17, -v17, s[0:1]
	v_mov_b32_e32 v5, v9
	v_mov_b32_e32 v9, v11
	v_mov_b32_e32 v13, v10
	v_pk_mul_f32 v[16:17], v[4:5], v[8:9]
	v_mov_b32_e32 v8, v116
	v_mov_b32_e32 v9, v117
	v_mov_b32_e32 v10, v118
	v_mov_b32_e32 v11, v119
	v_cndmask_b32_e64 v4, v21, -v21, s[0:1]
	v_mov_b32_e32 v21, v7
	v_mov_b32_e32 v7, v4
	s_waitcnt vmcnt(4) lgkmcnt(0)
	v_mov_b32_e32 v18, v9
	v_mov_b32_e32 v9, v11
	v_pk_mul_f32 v[8:9], v[6:7], v[8:9]
	v_mov_b32_e32 v4, v214
	v_mov_b32_e32 v5, v215
	v_mov_b32_e32 v6, v216
	v_mov_b32_e32 v7, v217
	v_mov_b32_e32 v19, v10
	s_waitcnt vmcnt(4) lgkmcnt(0)
	v_mov_b32_e32 v10, v5
	v_cndmask_b32_e64 v5, v23, -v23, s[0:1]
	v_mov_b32_e32 v23, v1
	v_mov_b32_e32 v1, v5
	v_mov_b32_e32 v5, v7
	v_mov_b32_e32 v11, v6
	v_pk_mul_f32 v[0:1], v[0:1], v[4:5]
	v_mov_b32_e32 v4, v246
	v_mov_b32_e32 v5, v247
	v_mov_b32_e32 v6, v248
	v_mov_b32_e32 v7, v249
	v_pk_fma_f32 v[0:1], v[22:23], v[10:11], v[0:1]
	s_waitcnt vmcnt(4) lgkmcnt(0)
	v_mul_f32_e32 v2, v2, v4
	v_cndmask_b32_e64 v4, v25, -v25, s[0:1]
	v_mul_f32_e32 v26, v4, v5
	v_cndmask_b32_e64 v5, v30, -v30, s[0:1]
	v_mov_b32_e32 v4, v3
	v_pk_mul_f32 v[4:5], v[4:5], v[6:7]
	v_pk_fma_f32 v[6:7], v[20:21], v[18:19], v[8:9]
	v_mov_b32_e32 v3, v4
	v_mov_b32_e32 v27, v5
	v_pk_fma_f32 v[4:5], v[14:15], v[12:13], v[16:17]
	v_pk_add_f32 v[2:3], v[2:3], v[26:27]

;   DI void operator()(int mt, int nt, int wm, int wn, int r, int h, f32x16 (&acc)[WM][2]) const {
;     ...
;       for (int j = 0; j < 8; ++j) {
;         const int id = tid + 256 * j;
;         const int lr = id >> 4, cc = id & 15;
;         const int row = mt * (WM * 64) + (lr >> 6) * (WM * 32) + ps * 64 + (lr & 63);
;         const int col0 = nt * 128 + cc * 8;
;         if (col0 < PW) {
;           const int t = row % NTOK;
;           const int ropemode = (t >= NCTX) ? ropemode0 : 0;
;           const float4 a0 = *(const float4*)(T + lr * LD + cc * 8), a1 = *(const float4*)(T + lr * LD + cc * 8 + 4);
;           const float4 b0 = *(const float4*)(bias + col0), b1 = *(const float4*)(bias + col0 + 4);
;           float v[8] = {a0.x + b0.x, a0.y + b0.y, a0.z + b0.z, a0.w + b0.w, a1.x + b1.x, a1.y + b1.y, a1.z + b1.z, a1.w + b1.w};
;           if (ropemode != 0) {
;             const int pc = (ropemode == 1) ? (cc ^ 1) : (cc ^ 2);
;             const float4 p0 = *(const float4*)(T + lr * LD + pc * 8), p1 = *(const float4*)(T + lr * LD + pc * 8 + 4);
;             const float4 c0 = *(const float4*)(bias + nt * 128 + pc * 8), c1 = *(const float4*)(bias + nt * 128 + pc * 8 + 4);
.LBB0_299:
	s_or_b64 exec, exec, s[8:9]
	v_add_u32_e32 v30, s43, v150
	s_and_saveexec_b64 s[8:9], s[6:7]
	s_cbranch_execz .LBB0_308
	v_or_b32_e32 v24, v30, v138
	v_mul_hi_i32 v16, v24, s55
	ds_read_b128 v[4:7], v140
	ds_read_b128 v[12:15], v140 offset:16
	v_lshrrev_b32_e32 v17, 31, v16
	v_ashrrev_i32_e32 v16, 9, v16
	v_add_u32_e32 v16, v16, v17
	v_mul_i32_i24_e32 v16, 0x900, v16
	v_sub_u32_e32 v25, v24, v16
	s_xor_b64 s[26:27], s[46:47], -1
	v_cmp_lt_i32_e32 vcc, s62, v25
	s_and_b64 s[28:29], vcc, s[26:27]
	s_waitcnt lgkmcnt(0)
	v_pk_add_f32 v[4:5], v[4:5], v[220:221]
	v_pk_add_f32 v[6:7], v[6:7], v[222:223]
	v_pk_add_f32 v[0:1], v[12:13], v[224:225]
	v_pk_add_f32 v[2:3], v[14:15], v[226:227]
	s_and_saveexec_b64 s[26:27], s[28:29]
	s_cbranch_execz .LBB0_306
	s_lshl_b64 s[28:29], s[24:25], 2
	s_add_u32 s28, s14, s28
	v_lshlrev_b32_e32 v12, 2, v132
	s_addc_u32 s29, s15, s29
	v_add_u32_e32 v12, v104, v12
	ds_read_b128 v[20:23], v12
	ds_read_b128 v[12:15], v12 offset:16
	v_add_u32_e32 v26, 0xffffff00, v25
	v_lshrrev_b32_e32 v26, 6, v26
	v_and_b32_e32 v25, 63, v25
	v_cndmask_b32_e64 v25, v25, v26, s[4:5]
	s_andn2_b64 vcc, exec, s[44:45]
	s_mov_b64 s[28:29], -1
	s_cbranch_vccnz .LBB0_303
	v_lshlrev_b32_e32 v160, 6, v25
	v_lshl_add_u64 v[26:27], s[18:19], 0, v[160:161]
	s_mov_b64 s[28:29], 0

;   DI void operator()(int mt, int nt, int wm, int wn, int r, int h, f32x16 (&acc)[WM][2]) const {
;     ...
;         const int lr = id >> 4, cc = id & 15;
;         const int row = mt * (WM * 64) + (lr >> 6) * (WM * 32) + ps * 64 + (lr & 63);
;         const int col0 = nt * 128 + cc * 8;
;         if (col0 < PW) {
;           const int t = row % NTOK;
;           const int ropemode = (t >= NCTX) ? ropemode0 : 0;
;           const float4 a0 = *(const float4*)(T + lr * LD + cc * 8), a1 = *(const float4*)(T + lr * LD + cc * 8 + 4);
;           const float4 b0 = *(const float4*)(bias + col0), b1 = *(const float4*)(bias + col0 + 4);
;           float v[8] = {a0.x + b0.x, a0.y + b0.y, a0.z + b0.z, a0.w + b0.w, a1.x + b1.x, a1.y + b1.y, a1.z + b1.z, a1.w + b1.w};
;           if (ropemode != 0) {
;             const int pc = (ropemode == 1) ? (cc ^ 1) : (cc ^ 2);
;             const float4 p0 = *(const float4*)(T + lr * LD + pc * 8), p1 = *(const float4*)(T + lr * LD + pc * 8 + 4);
;             const float4 c0 = *(const float4*)(bias + nt * 128 + pc * 8), c1 = *(const float4*)(bias + nt * 128 + pc * 8 + 4);
;             const float pr[8] = {p0.x + c0.x, p0.y + c0.y, p0.z + c0.z, p0.w + c0.w, p1.x + c1.x, p1.y + c1.y, p1.z + c1.z, p1.w + c1.w};
;             const int tok = t - NCTX;
;             const int q = (ropemode == 1) ? (cc & 3) : ((cc & 7) >> 1);
;             const int pos = (q < 2) ? (tok >> 6) : (tok & 63);
;             const float2* tab = (ropemode == 1) ? (T32 + pos * 8) : (T64 + pos * 16 + (cc & 1) * 8);
.LBB0_305:
	v_add_u32_e32 v122, 0x300, v204
	v_ashrrev_i32_e32 v124, 4, v122
	v_ashrrev_i32_e32 v122, 3, v122
	v_and_b32_e32 v122, 0xffffff80, v122
	v_and_b32_e32 v124, 63, v124
	v_add_u32_e32 v122, s43, v122
	v_or_b32_e32 v122, v122, v124
	v_mul_hi_i32 v124, v122, s55
	v_lshrrev_b32_e32 v160, 31, v124
	v_ashrrev_i32_e32 v124, 9, v124
	v_add_u32_e32 v124, v124, v160
	v_mul_i32_i24_e32 v124, 0x900, v124
	v_sub_u32_e32 v122, v122, v124
	v_add_u32_e32 v124, 0xffffff00, v122
	v_lshrrev_b32_e32 v124, 6, v124
	v_and_b32_e32 v122, 63, v122
	v_cndmask_b32_e64 v122, v122, v124, s[4:5]
	s_andn2_b64 vcc, exec, s[44:45]
	s_cbranch_vccnz .Lrp_b_1_2
	v_lshlrev_b32_e32 v160, 6, v122
	v_lshl_add_u64 v[120:121], s[18:19], 0, v[160:161]
	s_branch .Lrp_l_1_2

;   DI void operator()(int mt, int nt, int wm, int wn, int r, int h, f32x16 (&acc)[WM][2]) const {
;     ...
;           if (ropemode != 0) {
;             const int pc = (ropemode == 1) ? (cc ^ 1) : (cc ^ 2);
;             const float4 p0 = *(const float4*)(T + lr * LD + pc * 8), p1 = *(const float4*)(T + lr * LD + pc * 8 + 4);
;             const float4 c0 = *(const float4*)(bias + nt * 128 + pc * 8), c1 = *(const float4*)(bias + nt * 128 + pc * 8 + 4);
;             const float pr[8] = {p0.x + c0.x, p0.y + c0.y, p0.z + c0.z, p0.w + c0.w, p1.x + c1.x, p1.y + c1.y, p1.z + c1.z, p1.w + c1.w};
;             const int tok = t - NCTX;
;             const int q = (ropemode == 1) ? (cc & 3) : ((cc & 7) >> 1);
;             const int pos = (q < 2) ? (tok >> 6) : (tok & 63);
;             const float2* tab = (ropemode == 1) ? (T32 + pos * 8) : (T64 + pos * 16 + (cc & 1) * 8);
;             const float sgn = (q & 1) ? 1.f : -1.f;
; #pragma unroll
;             for (int k = 0; k < 8; ++k) { const float2 cs = tab[k]; v[k] = v[k] * cs.x + sgn * pr[k] * cs.y; }
.Lrp_l_1_2:
	global_load_dwordx4 v[112:115], v[120:121], off
	global_load_dwordx4 v[116:119], v[120:121], off offset:16
	global_load_dwordx4 v[214:217], v[120:121], off offset:32
	global_load_dwordx4 v[246:249], v[120:121], off offset:48
	s_waitcnt vmcnt(4) lgkmcnt(1)
	v_add_f32_e32 v16, v20, v213
	v_add_f32_e32 v17, v21, v218
	v_add_f32_e32 v20, v22, v219
	v_add_f32_e32 v21, v23, v245
	s_waitcnt lgkmcnt(0)
	v_add_f32_e32 v22, v12, v250
	v_add_f32_e32 v23, v13, v251
	v_add_f32_e32 v25, v14, v126
	v_add_f32_e32 v31, v15, v127
	v_mov_b32_e32 v8, v228
	v_mov_b32_e32 v9, v229
	v_mov_b32_e32 v10, v230
	v_mov_b32_e32 v11, v231
	v_mov_b32_e32 v15, v5
	v_cndmask_b32_e64 v14, v16, -v16, s[0:1]
	v_cndmask_b32_e64 v20, v20, -v20, s[0:1]
	v_cndmask_b32_e64 v22, v22, -v22, s[0:1]
	s_waitcnt vmcnt(4) lgkmcnt(0)
	v_mov_b32_e32 v12, v9
	v_cndmask_b32_e64 v9, v17, -v17, s[0:1]
	v_mov_b32_e32 v5, v9
	v_mov_b32_e32 v9, v11
	v_mov_b32_e32 v13, v10
	v_pk_mul_f32 v[16:17], v[4:5], v[8:9]
	v_mov_b32_e32 v8, v232
	v_mov_b32_e32 v9, v233
	v_mov_b32_e32 v10, v234
	v_mov_b32_e32 v11, v235
	v_cndmask_b32_e64 v4, v21, -v21, s[0:1]
	v_mov_b32_e32 v21, v7
	v_mov_b32_e32 v7, v4
	s_waitcnt vmcnt(4) lgkmcnt(0)
	v_mov_b32_e32 v18, v9
	v_mov_b32_e32 v9, v11
	v_pk_mul_f32 v[8:9], v[6:7], v[8:9]
	v_mov_b32_e32 v4, v236
	v_mov_b32_e32 v5, v237
	v_mov_b32_e32 v6, v238
	v_mov_b32_e32 v7, v239
	v_mov_b32_e32 v19, v10
	s_waitcnt vmcnt(4) lgkmcnt(0)
	v_mov_b32_e32 v10, v5
	v_cndmask_b32_e64 v5, v23, -v23, s[0:1]
	v_mov_b32_e32 v23, v1
	v_mov_b32_e32 v1, v5
	v_mov_b32_e32 v5, v7
	v_mov_b32_e32 v11, v6
	v_pk_mul_f32 v[0:1], v[0:1], v[4:5]
	v_mov_b32_e32 v4, v240
	v_mov_b32_e32 v5, v241
	v_mov_b32_e32 v6, v242
	v_mov_b32_e32 v7, v243
	v_pk_fma_f32 v[0:1], v[22:23], v[10:11], v[0:1]
	s_waitcnt vmcnt(4) lgkmcnt(0)
	v_mul_f32_e32 v2, v2, v4
	v_cndmask_b32_e64 v4, v25, -v25, s[0:1]
	v_mul_f32_e32 v26, v4, v5
	v_cndmask_b32_e64 v5, v31, -v31, s[0:1]
	v_mov_b32_e32 v4, v3
	v_pk_mul_f32 v[4:5], v[4:5], v[6:7]
	v_pk_fma_f32 v[6:7], v[20:21], v[18:19], v[8:9]
	v_mov_b32_e32 v3, v4
	v_mov_b32_e32 v27, v5
	v_pk_fma_f32 v[4:5], v[14:15], v[12:13], v[16:17]
	v_pk_add_f32 v[2:3], v[2:3], v[26:27]

;   DI void operator()(int mt, int nt, int wm, int wn, int r, int h, f32x16 (&acc)[WM][2]) const {
;     ...
;       for (int j = 0; j < 8; ++j) {
;         const int id = tid + 256 * j;
;         const int lr = id >> 4, cc = id & 15;
;         const int row = mt * (WM * 64) + (lr >> 6) * (WM * 32) + ps * 64 + (lr & 63);
;         const int col0 = nt * 128 + cc * 8;
;         if (col0 < PW) {
;           const int t = row % NTOK;
;           const int ropemode = (t >= NCTX) ? ropemode0 : 0;
;           const float4 a0 = *(const float4*)(T + lr * LD + cc * 8), a1 = *(const float4*)(T + lr * LD + cc * 8 + 4);
;           const float4 b0 = *(const float4*)(bias + col0), b1 = *(const float4*)(bias + col0 + 4);
;           float v[8] = {a0.x + b0.x, a0.y + b0.y, a0.z + b0.z, a0.w + b0.w, a1.x + b1.x, a1.y + b1.y, a1.z + b1.z, a1.w + b1.w};
;           if (ropemode != 0) {
;             const int pc = (ropemode == 1) ? (cc ^ 1) : (cc ^ 2);
;             const float4 p0 = *(const float4*)(T + lr * LD + pc * 8), p1 = *(const float4*)(T + lr * LD + pc * 8 + 4);
;             const float4 c0 = *(const float4*)(bias + nt * 128 + pc * 8), c1 = *(const float4*)(bias + nt * 128 + pc * 8 + 4);
.LBB0_308:
	s_or_b64 exec, exec, s[8:9]
	v_add_u32_e32 v31, s43, v171
	s_and_saveexec_b64 s[8:9], s[6:7]
	s_cbranch_execz .LBB0_317
	v_or_b32_e32 v24, v31, v145
	v_mul_hi_i32 v16, v24, s55
	ds_read_b128 v[4:7], v146
	ds_read_b128 v[12:15], v146 offset:16
	v_lshrrev_b32_e32 v17, 31, v16
	v_ashrrev_i32_e32 v16, 9, v16
	v_add_u32_e32 v16, v16, v17
	v_mul_i32_i24_e32 v16, 0x900, v16
	v_sub_u32_e32 v25, v24, v16
	s_xor_b64 s[26:27], s[46:47], -1
	v_cmp_lt_i32_e32 vcc, s62, v25
	s_and_b64 s[28:29], vcc, s[26:27]
	s_waitcnt lgkmcnt(0)
	v_pk_add_f32 v[4:5], v[4:5], v[220:221]
	v_pk_add_f32 v[6:7], v[6:7], v[222:223]
	v_pk_add_f32 v[0:1], v[12:13], v[224:225]
	v_pk_add_f32 v[2:3], v[14:15], v[226:227]
	s_and_saveexec_b64 s[26:27], s[28:29]
	s_cbranch_execz .LBB0_315
	s_lshl_b64 s[28:29], s[24:25], 2
	s_add_u32 s28, s14, s28
	v_lshlrev_b32_e32 v12, 2, v132
	s_addc_u32 s29, s15, s29
	v_add_u32_e32 v12, v105, v12
	ds_read_b128 v[20:23], v12
	ds_read_b128 v[12:15], v12 offset:16
	v_add_u32_e32 v26, 0xffffff00, v25
	v_lshrrev_b32_e32 v26, 6, v26
	v_and_b32_e32 v25, 63, v25
	v_cndmask_b32_e64 v25, v25, v26, s[4:5]
	s_andn2_b64 vcc, exec, s[44:45]
	s_mov_b64 s[28:29], -1
	s_cbranch_vccnz .LBB0_312
	v_lshlrev_b32_e32 v160, 6, v25
	v_lshl_add_u64 v[26:27], s[18:19], 0, v[160:161]
	s_mov_b64 s[28:29], 0

;   DI void operator()(int mt, int nt, int wm, int wn, int r, int h, f32x16 (&acc)[WM][2]) const {
;     ...
;         const int lr = id >> 4, cc = id & 15;
;         const int row = mt * (WM * 64) + (lr >> 6) * (WM * 32) + ps * 64 + (lr & 63);
;         const int col0 = nt * 128 + cc * 8;
;         if (col0 < PW) {
;           const int t = row % NTOK;
;           const int ropemode = (t >= NCTX) ? ropemode0 : 0;
;           const float4 a0 = *(const float4*)(T + lr * LD + cc * 8), a1 = *(const float4*)(T + lr * LD + cc * 8 + 4);
;           const float4 b0 = *(const float4*)(bias + col0), b1 = *(const float4*)(bias + col0 + 4);
;           float v[8] = {a0.x + b0.x, a0.y + b0.y, a0.z + b0.z, a0.w + b0.w, a1.x + b1.x, a1.y + b1.y, a1.z + b1.z, a1.w + b1.w};
;           if (ropemode != 0) {
;             const int pc = (ropemode == 1) ? (cc ^ 1) : (cc ^ 2);
;             const float4 p0 = *(const float4*)(T + lr * LD + pc * 8), p1 = *(const float4*)(T + lr * LD + pc * 8 + 4);
;             const float4 c0 = *(const float4*)(bias + nt * 128 + pc * 8), c1 = *(const float4*)(bias + nt * 128 + pc * 8 + 4);
;             const float pr[8] = {p0.x + c0.x, p0.y + c0.y, p0.z + c0.z, p0.w + c0.w, p1.x + c1.x, p1.y + c1.y, p1.z + c1.z, p1.w + c1.w};
;             const int tok = t - NCTX;
;             const int q = (ropemode == 1) ? (cc & 3) : ((cc & 7) >> 1);
;             const int pos = (q < 2) ? (tok >> 6) : (tok & 63);
;             const float2* tab = (ropemode == 1) ? (T32 + pos * 8) : (T64 + pos * 16 + (cc & 1) * 8);
.LBB0_314:
	v_add_u32_e32 v122, 0x400, v204
	v_ashrrev_i32_e32 v124, 4, v122
	v_ashrrev_i32_e32 v122, 3, v122
	v_and_b32_e32 v122, 0xffffff80, v122
	v_and_b32_e32 v124, 63, v124
	v_add_u32_e32 v122, s43, v122
	v_or_b32_e32 v122, v122, v124
	v_mul_hi_i32 v124, v122, s55
	v_lshrrev_b32_e32 v160, 31, v124
	v_ashrrev_i32_e32 v124, 9, v124
	v_add_u32_e32 v124, v124, v160
	v_mul_i32_i24_e32 v124, 0x900, v124
	v_sub_u32_e32 v122, v122, v124
	v_add_u32_e32 v124, 0xffffff00, v122
	v_lshrrev_b32_e32 v124, 6, v124
	v_and_b32_e32 v122, 63, v122
	v_cndmask_b32_e64 v122, v122, v124, s[4:5]
	s_andn2_b64 vcc, exec, s[44:45]
	s_cbranch_vccnz .Lrp_b_1_3
	v_lshlrev_b32_e32 v160, 6, v122
	v_lshl_add_u64 v[120:121], s[18:19], 0, v[160:161]
	s_branch .Lrp_l_1_3

;   DI void operator()(int mt, int nt, int wm, int wn, int r, int h, f32x16 (&acc)[WM][2]) const {
;     ...
;           if (ropemode != 0) {
;             const int pc = (ropemode == 1) ? (cc ^ 1) : (cc ^ 2);
;             const float4 p0 = *(const float4*)(T + lr * LD + pc * 8), p1 = *(const float4*)(T + lr * LD + pc * 8 + 4);
;             const float4 c0 = *(const float4*)(bias + nt * 128 + pc * 8), c1 = *(const float4*)(bias + nt * 128 + pc * 8 + 4);
;             const float pr[8] = {p0.x + c0.x, p0.y + c0.y, p0.z + c0.z, p0.w + c0.w, p1.x + c1.x, p1.y + c1.y, p1.z + c1.z, p1.w + c1.w};
;             const int tok = t - NCTX;
;             const int q = (ropemode == 1) ? (cc & 3) : ((cc & 7) >> 1);
;             const int pos = (q < 2) ? (tok >> 6) : (tok & 63);
;             const float2* tab = (ropemode == 1) ? (T32 + pos * 8) : (T64 + pos * 16 + (cc & 1) * 8);
;             const float sgn = (q & 1) ? 1.f : -1.f;
; #pragma unroll
;             for (int k = 0; k < 8; ++k) { const float2 cs = tab[k]; v[k] = v[k] * cs.x + sgn * pr[k] * cs.y; }
.Lrp_l_1_3:
	global_load_dwordx4 v[228:231], v[120:121], off
	global_load_dwordx4 v[232:235], v[120:121], off offset:16
	global_load_dwordx4 v[236:239], v[120:121], off offset:32
	global_load_dwordx4 v[240:243], v[120:121], off offset:48
	s_waitcnt vmcnt(4) lgkmcnt(1)
	v_add_f32_e32 v16, v20, v213
	v_add_f32_e32 v17, v21, v218
	v_add_f32_e32 v20, v22, v219
	v_add_f32_e32 v21, v23, v245
	s_waitcnt lgkmcnt(0)
	v_add_f32_e32 v22, v12, v250
	v_add_f32_e32 v23, v13, v251
	v_add_f32_e32 v25, v14, v126
	v_add_f32_e32 v32, v15, v127
	v_mov_b32_e32 v8, v112
	v_mov_b32_e32 v9, v113
	v_mov_b32_e32 v10, v114
	v_mov_b32_e32 v11, v115
	v_mov_b32_e32 v15, v5
	v_cndmask_b32_e64 v14, v16, -v16, s[0:1]
	v_cndmask_b32_e64 v20, v20, -v20, s[0:1]
	v_cndmask_b32_e64 v22, v22, -v22, s[0:1]
	s_waitcnt vmcnt(4) lgkmcnt(0)
	v_mov_b32_e32 v12, v9
	v_cndmask_b32_e64 v9, v17, -v17, s[0:1]
	v_mov_b32_e32 v5, v9
	v_mov_b32_e32 v9, v11
	v_mov_b32_e32 v13, v10
	v_pk_mul_f32 v[16:17], v[4:5], v[8:9]
	v_mov_b32_e32 v8, v116
	v_mov_b32_e32 v9, v117
	v_mov_b32_e32 v10, v118
	v_mov_b32_e32 v11, v119
	v_cndmask_b32_e64 v4, v21, -v21, s[0:1]
	v_mov_b32_e32 v21, v7
	v_mov_b32_e32 v7, v4
	s_waitcnt vmcnt(4) lgkmcnt(0)
	v_mov_b32_e32 v18, v9
	v_mov_b32_e32 v9, v11
	v_pk_mul_f32 v[8:9], v[6:7], v[8:9]
	v_mov_b32_e32 v4, v214
	v_mov_b32_e32 v5, v215
	v_mov_b32_e32 v6, v216
	v_mov_b32_e32 v7, v217
	v_mov_b32_e32 v19, v10
	s_waitcnt vmcnt(4) lgkmcnt(0)
	v_mov_b32_e32 v10, v5
	v_cndmask_b32_e64 v5, v23, -v23, s[0:1]
	v_mov_b32_e32 v23, v1
	v_mov_b32_e32 v1, v5
	v_mov_b32_e32 v5, v7
	v_mov_b32_e32 v11, v6
	v_pk_mul_f32 v[0:1], v[0:1], v[4:5]
	v_mov_b32_e32 v4, v246
	v_mov_b32_e32 v5, v247
	v_mov_b32_e32 v6, v248
	v_mov_b32_e32 v7, v249
	v_pk_fma_f32 v[0:1], v[22:23], v[10:11], v[0:1]
	s_waitcnt vmcnt(4) lgkmcnt(0)
	v_mul_f32_e32 v2, v2, v4
	v_cndmask_b32_e64 v4, v25, -v25, s[0:1]
	v_mul_f32_e32 v26, v4, v5
	v_cndmask_b32_e64 v5, v32, -v32, s[0:1]
	v_mov_b32_e32 v4, v3
	v_pk_mul_f32 v[4:5], v[4:5], v[6:7]
	v_pk_fma_f32 v[6:7], v[20:21], v[18:19], v[8:9]
	v_mov_b32_e32 v3, v4
	v_mov_b32_e32 v27, v5
	v_pk_fma_f32 v[4:5], v[14:15], v[12:13], v[16:17]
	v_pk_add_f32 v[2:3], v[2:3], v[26:27]

;   DI void operator()(int mt, int nt, int wm, int wn, int r, int h, f32x16 (&acc)[WM][2]) const {
;     ...
;       for (int j = 0; j < 8; ++j) {
;         const int id = tid + 256 * j;
;         const int lr = id >> 4, cc = id & 15;
;         const int row = mt * (WM * 64) + (lr >> 6) * (WM * 32) + ps * 64 + (lr & 63);
;         const int col0 = nt * 128 + cc * 8;
;         if (col0 < PW) {
;           const int t = row % NTOK;
;           const int ropemode = (t >= NCTX) ? ropemode0 : 0;
;           const float4 a0 = *(const float4*)(T + lr * LD + cc * 8), a1 = *(const float4*)(T + lr * LD + cc * 8 + 4);
;           const float4 b0 = *(const float4*)(bias + col0), b1 = *(const float4*)(bias + col0 + 4);
;           float v[8] = {a0.x + b0.x, a0.y + b0.y, a0.z + b0.z, a0.w + b0.w, a1.x + b1.x, a1.y + b1.y, a1.z + b1.z, a1.w + b1.w};
;           if (ropemode != 0) {
;             const int pc = (ropemode == 1) ? (cc ^ 1) : (cc ^ 2);
;             const float4 p0 = *(const float4*)(T + lr * LD + pc * 8), p1 = *(const float4*)(T + lr * LD + pc * 8 + 4);
;             const float4 c0 = *(const float4*)(bias + nt * 128 + pc * 8), c1 = *(const float4*)(bias + nt * 128 + pc * 8 + 4);
.LBB0_317:
	s_or_b64 exec, exec, s[8:9]
	v_add_u32_e32 v32, s43, v198
	s_and_saveexec_b64 s[8:9], s[6:7]
	s_cbranch_execz .LBB0_326
	v_or_b32_e32 v24, v32, v148
	v_mul_hi_i32 v16, v24, s55
	ds_read_b128 v[4:7], v149
	ds_read_b128 v[12:15], v149 offset:16
	v_lshrrev_b32_e32 v17, 31, v16
	v_ashrrev_i32_e32 v16, 9, v16
	v_add_u32_e32 v16, v16, v17
	v_mul_i32_i24_e32 v16, 0x900, v16
	v_sub_u32_e32 v25, v24, v16
	s_xor_b64 s[26:27], s[46:47], -1
	v_cmp_lt_i32_e32 vcc, s62, v25
	s_and_b64 s[28:29], vcc, s[26:27]
	s_waitcnt lgkmcnt(0)
	v_pk_add_f32 v[4:5], v[4:5], v[220:221]
	v_pk_add_f32 v[6:7], v[6:7], v[222:223]
	v_pk_add_f32 v[0:1], v[12:13], v[224:225]
	v_pk_add_f32 v[2:3], v[14:15], v[226:227]
	s_and_saveexec_b64 s[26:27], s[28:29]
	s_cbranch_execz .LBB0_324
	s_lshl_b64 s[28:29], s[24:25], 2
	s_add_u32 s28, s14, s28
	v_lshlrev_b32_e32 v12, 2, v132
	s_addc_u32 s29, s15, s29
	v_add_u32_e32 v12, v106, v12
	ds_read_b128 v[20:23], v12
	ds_read_b128 v[12:15], v12 offset:16
	v_add_u32_e32 v26, 0xffffff00, v25
	v_lshrrev_b32_e32 v26, 6, v26
	v_and_b32_e32 v25, 63, v25
	v_cndmask_b32_e64 v25, v25, v26, s[4:5]
	s_andn2_b64 vcc, exec, s[44:45]
	s_mov_b64 s[28:29], -1
	s_cbranch_vccnz .LBB0_321
	v_lshlrev_b32_e32 v160, 6, v25
	v_lshl_add_u64 v[26:27], s[18:19], 0, v[160:161]
	s_mov_b64 s[28:29], 0

;   DI void operator()(int mt, int nt, int wm, int wn, int r, int h, f32x16 (&acc)[WM][2]) const {
;     ...
;         const int lr = id >> 4, cc = id & 15;
;         const int row = mt * (WM * 64) + (lr >> 6) * (WM * 32) + ps * 64 + (lr & 63);
;         const int col0 = nt * 128 + cc * 8;
;         if (col0 < PW) {
;           const int t = row % NTOK;
;           const int ropemode = (t >= NCTX) ? ropemode0 : 0;
;           const float4 a0 = *(const float4*)(T + lr * LD + cc * 8), a1 = *(const float4*)(T + lr * LD + cc * 8 + 4);
;           const float4 b0 = *(const float4*)(bias + col0), b1 = *(const float4*)(bias + col0 + 4);
;           float v[8] = {a0.x + b0.x, a0.y + b0.y, a0.z + b0.z, a0.w + b0.w, a1.x + b1.x, a1.y + b1.y, a1.z + b1.z, a1.w + b1.w};
;           if (ropemode != 0) {
;             const int pc = (ropemode == 1) ? (cc ^ 1) : (cc ^ 2);
;             const float4 p0 = *(const float4*)(T + lr * LD + pc * 8), p1 = *(const float4*)(T + lr * LD + pc * 8 + 4);
;             const float4 c0 = *(const float4*)(bias + nt * 128 + pc * 8), c1 = *(const float4*)(bias + nt * 128 + pc * 8 + 4);
;             const float pr[8] = {p0.x + c0.x, p0.y + c0.y, p0.z + c0.z, p0.w + c0.w, p1.x + c1.x, p1.y + c1.y, p1.z + c1.z, p1.w + c1.w};
;             const int tok = t - NCTX;
;             const int q = (ropemode == 1) ? (cc & 3) : ((cc & 7) >> 1);
;             const int pos = (q < 2) ? (tok >> 6) : (tok & 63);
;             const float2* tab = (ropemode == 1) ? (T32 + pos * 8) : (T64 + pos * 16 + (cc & 1) * 8);
.LBB0_323:
	v_add_u32_e32 v122, 0x500, v204
	v_ashrrev_i32_e32 v124, 4, v122
	v_ashrrev_i32_e32 v122, 3, v122
	v_and_b32_e32 v122, 0xffffff80, v122
	v_and_b32_e32 v124, 63, v124
	v_add_u32_e32 v122, s43, v122
	v_or_b32_e32 v122, v122, v124
	v_mul_hi_i32 v124, v122, s55
	v_lshrrev_b32_e32 v160, 31, v124
	v_ashrrev_i32_e32 v124, 9, v124
	v_add_u32_e32 v124, v124, v160
	v_mul_i32_i24_e32 v124, 0x900, v124
	v_sub_u32_e32 v122, v122, v124
	v_add_u32_e32 v124, 0xffffff00, v122
	v_lshrrev_b32_e32 v124, 6, v124
	v_and_b32_e32 v122, 63, v122
	v_cndmask_b32_e64 v122, v122, v124, s[4:5]
	s_andn2_b64 vcc, exec, s[44:45]
	s_cbranch_vccnz .Lrp_b_1_4
	v_lshlrev_b32_e32 v160, 6, v122
	v_lshl_add_u64 v[120:121], s[18:19], 0, v[160:161]
	s_branch .Lrp_l_1_4

;   DI void operator()(int mt, int nt, int wm, int wn, int r, int h, f32x16 (&acc)[WM][2]) const {
;     ...
;           if (ropemode != 0) {
;             const int pc = (ropemode == 1) ? (cc ^ 1) : (cc ^ 2);
;             const float4 p0 = *(const float4*)(T + lr * LD + pc * 8), p1 = *(const float4*)(T + lr * LD + pc * 8 + 4);
;             const float4 c0 = *(const float4*)(bias + nt * 128 + pc * 8), c1 = *(const float4*)(bias + nt * 128 + pc * 8 + 4);
;             const float pr[8] = {p0.x + c0.x, p0.y + c0.y, p0.z + c0.z, p0.w + c0.w, p1.x + c1.x, p1.y + c1.y, p1.z + c1.z, p1.w + c1.w};
;             const int tok = t - NCTX;
;             const int q = (ropemode == 1) ? (cc & 3) : ((cc & 7) >> 1);
;             const int pos = (q < 2) ? (tok >> 6) : (tok & 63);
;             const float2* tab = (ropemode == 1) ? (T32 + pos * 8) : (T64 + pos * 16 + (cc & 1) * 8);
;             const float sgn = (q & 1) ? 1.f : -1.f;
; #pragma unroll
;             for (int k = 0; k < 8; ++k) { const float2 cs = tab[k]; v[k] = v[k] * cs.x + sgn * pr[k] * cs.y; }
.Lrp_l_1_4:
	global_load_dwordx4 v[112:115], v[120:121], off
	global_load_dwordx4 v[116:119], v[120:121], off offset:16
	global_load_dwordx4 v[214:217], v[120:121], off offset:32
	global_load_dwordx4 v[246:249], v[120:121], off offset:48
	s_waitcnt vmcnt(4) lgkmcnt(1)
	v_add_f32_e32 v16, v20, v213
	v_add_f32_e32 v17, v21, v218
	v_add_f32_e32 v20, v22, v219
	v_add_f32_e32 v21, v23, v245
	s_waitcnt lgkmcnt(0)
	v_add_f32_e32 v22, v12, v250
	v_add_f32_e32 v23, v13, v251
	v_add_f32_e32 v25, v14, v126
	v_add_f32_e32 v33, v15, v127
	v_mov_b32_e32 v8, v228
	v_mov_b32_e32 v9, v229
	v_mov_b32_e32 v10, v230
	v_mov_b32_e32 v11, v231
	v_mov_b32_e32 v15, v5
	v_cndmask_b32_e64 v14, v16, -v16, s[0:1]
	v_cndmask_b32_e64 v20, v20, -v20, s[0:1]
	v_cndmask_b32_e64 v22, v22, -v22, s[0:1]
	s_waitcnt vmcnt(4) lgkmcnt(0)
	v_mov_b32_e32 v12, v9
	v_cndmask_b32_e64 v9, v17, -v17, s[0:1]
	v_mov_b32_e32 v5, v9
	v_mov_b32_e32 v9, v11
	v_mov_b32_e32 v13, v10
	v_pk_mul_f32 v[16:17], v[4:5], v[8:9]
	v_mov_b32_e32 v8, v232
	v_mov_b32_e32 v9, v233
	v_mov_b32_e32 v10, v234
	v_mov_b32_e32 v11, v235
	v_cndmask_b32_e64 v4, v21, -v21, s[0:1]
	v_mov_b32_e32 v21, v7
	v_mov_b32_e32 v7, v4
	s_waitcnt vmcnt(4) lgkmcnt(0)
	v_mov_b32_e32 v18, v9
	v_mov_b32_e32 v9, v11
	v_pk_mul_f32 v[8:9], v[6:7], v[8:9]
	v_mov_b32_e32 v4, v236
	v_mov_b32_e32 v5, v237
	v_mov_b32_e32 v6, v238
	v_mov_b32_e32 v7, v239
	v_mov_b32_e32 v19, v10
	s_waitcnt vmcnt(4) lgkmcnt(0)
	v_mov_b32_e32 v10, v5
	v_cndmask_b32_e64 v5, v23, -v23, s[0:1]
	v_mov_b32_e32 v23, v1
	v_mov_b32_e32 v1, v5
	v_mov_b32_e32 v5, v7
	v_mov_b32_e32 v11, v6
	v_pk_mul_f32 v[0:1], v[0:1], v[4:5]
	v_mov_b32_e32 v4, v240
	v_mov_b32_e32 v5, v241
	v_mov_b32_e32 v6, v242
	v_mov_b32_e32 v7, v243
	v_pk_fma_f32 v[0:1], v[22:23], v[10:11], v[0:1]
	s_waitcnt vmcnt(4) lgkmcnt(0)
	v_mul_f32_e32 v2, v2, v4
	v_cndmask_b32_e64 v4, v25, -v25, s[0:1]
	v_mul_f32_e32 v26, v4, v5
	v_cndmask_b32_e64 v5, v33, -v33, s[0:1]
	v_mov_b32_e32 v4, v3
	v_pk_mul_f32 v[4:5], v[4:5], v[6:7]
	v_pk_fma_f32 v[6:7], v[20:21], v[18:19], v[8:9]
	v_mov_b32_e32 v3, v4
	v_mov_b32_e32 v27, v5
	v_pk_fma_f32 v[4:5], v[14:15], v[12:13], v[16:17]
	v_pk_add_f32 v[2:3], v[2:3], v[26:27]

;   DI void operator()(int mt, int nt, int wm, int wn, int r, int h, f32x16 (&acc)[WM][2]) const {
;     ...
;       for (int j = 0; j < 8; ++j) {
;         const int id = tid + 256 * j;
;         const int lr = id >> 4, cc = id & 15;
;         const int row = mt * (WM * 64) + (lr >> 6) * (WM * 32) + ps * 64 + (lr & 63);
;         const int col0 = nt * 128 + cc * 8;
;         if (col0 < PW) {
;           const int t = row % NTOK;
;           const int ropemode = (t >= NCTX) ? ropemode0 : 0;
;           const float4 a0 = *(const float4*)(T + lr * LD + cc * 8), a1 = *(const float4*)(T + lr * LD + cc * 8 + 4);
;           const float4 b0 = *(const float4*)(bias + col0), b1 = *(const float4*)(bias + col0 + 4);
;           float v[8] = {a0.x + b0.x, a0.y + b0.y, a0.z + b0.z, a0.w + b0.w, a1.x + b1.x, a1.y + b1.y, a1.z + b1.z, a1.w + b1.w};
;           if (ropemode != 0) {
;             const int pc = (ropemode == 1) ? (cc ^ 1) : (cc ^ 2);
;             const float4 p0 = *(const float4*)(T + lr * LD + pc * 8), p1 = *(const float4*)(T + lr * LD + pc * 8 + 4);
;             const float4 c0 = *(const float4*)(bias + nt * 128 + pc * 8), c1 = *(const float4*)(bias + nt * 128 + pc * 8 + 4);
.LBB0_326:
	s_or_b64 exec, exec, s[8:9]
	v_add_u32_e32 v33, s43, v201
	s_and_saveexec_b64 s[8:9], s[6:7]
	s_cbranch_execz .LBB0_335
	v_or_b32_e32 v24, v33, v151
	v_mul_hi_i32 v16, v24, s55
	ds_read_b128 v[4:7], v170
	ds_read_b128 v[12:15], v170 offset:16
	v_lshrrev_b32_e32 v17, 31, v16
	v_ashrrev_i32_e32 v16, 9, v16
	v_add_u32_e32 v16, v16, v17
	v_mul_i32_i24_e32 v16, 0x900, v16
	v_sub_u32_e32 v25, v24, v16
	s_xor_b64 s[26:27], s[46:47], -1
	v_cmp_lt_i32_e32 vcc, s62, v25
	s_and_b64 s[28:29], vcc, s[26:27]
	s_waitcnt lgkmcnt(0)
	v_pk_add_f32 v[4:5], v[4:5], v[220:221]
	v_pk_add_f32 v[6:7], v[6:7], v[222:223]
	v_pk_add_f32 v[0:1], v[12:13], v[224:225]
	v_pk_add_f32 v[2:3], v[14:15], v[226:227]
	s_and_saveexec_b64 s[26:27], s[28:29]
	s_cbranch_execz .LBB0_333
	s_lshl_b64 s[28:29], s[24:25], 2
	s_add_u32 s28, s14, s28
	v_lshlrev_b32_e32 v12, 2, v132
	s_addc_u32 s29, s15, s29
	v_add_u32_e32 v12, v107, v12
	ds_read_b128 v[20:23], v12
	ds_read_b128 v[12:15], v12 offset:16
	v_add_u32_e32 v26, 0xffffff00, v25
	v_lshrrev_b32_e32 v26, 6, v26
	v_and_b32_e32 v25, 63, v25
	v_cndmask_b32_e64 v25, v25, v26, s[4:5]
	s_andn2_b64 vcc, exec, s[44:45]
	s_mov_b64 s[28:29], -1
	s_cbranch_vccnz .LBB0_330
	v_lshlrev_b32_e32 v160, 6, v25
	v_lshl_add_u64 v[26:27], s[18:19], 0, v[160:161]
	s_mov_b64 s[28:29], 0

;   DI void operator()(int mt, int nt, int wm, int wn, int r, int h, f32x16 (&acc)[WM][2]) const {
;     ...
;         const int lr = id >> 4, cc = id & 15;
;         const int row = mt * (WM * 64) + (lr >> 6) * (WM * 32) + ps * 64 + (lr & 63);
;         const int col0 = nt * 128 + cc * 8;
;         if (col0 < PW) {
;           const int t = row % NTOK;
;           const int ropemode = (t >= NCTX) ? ropemode0 : 0;
;           const float4 a0 = *(const float4*)(T + lr * LD + cc * 8), a1 = *(const float4*)(T + lr * LD + cc * 8 + 4);
;           const float4 b0 = *(const float4*)(bias + col0), b1 = *(const float4*)(bias + col0 + 4);
;           float v[8] = {a0.x + b0.x, a0.y + b0.y, a0.z + b0.z, a0.w + b0.w, a1.x + b1.x, a1.y + b1.y, a1.z + b1.z, a1.w + b1.w};
;           if (ropemode != 0) {
;             const int pc = (ropemode == 1) ? (cc ^ 1) : (cc ^ 2);
;             const float4 p0 = *(const float4*)(T + lr * LD + pc * 8), p1 = *(const float4*)(T + lr * LD + pc * 8 + 4);
;             const float4 c0 = *(const float4*)(bias + nt * 128 + pc * 8), c1 = *(const float4*)(bias + nt * 128 + pc * 8 + 4);
;             const float pr[8] = {p0.x + c0.x, p0.y + c0.y, p0.z + c0.z, p0.w + c0.w, p1.x + c1.x, p1.y + c1.y, p1.z + c1.z, p1.w + c1.w};
;             const int tok = t - NCTX;
;             const int q = (ropemode == 1) ? (cc & 3) : ((cc & 7) >> 1);
;             const int pos = (q < 2) ? (tok >> 6) : (tok & 63);
;             const float2* tab = (ropemode == 1) ? (T32 + pos * 8) : (T64 + pos * 16 + (cc & 1) * 8);
.LBB0_332:
	v_add_u32_e32 v122, 0x600, v204
	v_ashrrev_i32_e32 v124, 4, v122
	v_ashrrev_i32_e32 v122, 3, v122
	v_and_b32_e32 v122, 0xffffff80, v122
	v_and_b32_e32 v124, 63, v124
	v_add_u32_e32 v122, s43, v122
	v_or_b32_e32 v122, v122, v124
	v_mul_hi_i32 v124, v122, s55
	v_lshrrev_b32_e32 v160, 31, v124
	v_ashrrev_i32_e32 v124, 9, v124
	v_add_u32_e32 v124, v124, v160
	v_mul_i32_i24_e32 v124, 0x900, v124
	v_sub_u32_e32 v122, v122, v124
	v_add_u32_e32 v124, 0xffffff00, v122
	v_lshrrev_b32_e32 v124, 6, v124
	v_and_b32_e32 v122, 63, v122
	v_cndmask_b32_e64 v122, v122, v124, s[4:5]
	s_andn2_b64 vcc, exec, s[44:45]
	s_cbranch_vccnz .Lrp_b_1_5
	v_lshlrev_b32_e32 v160, 6, v122
	v_lshl_add_u64 v[120:121], s[18:19], 0, v[160:161]
	s_branch .Lrp_l_1_5

;   DI void operator()(int mt, int nt, int wm, int wn, int r, int h, f32x16 (&acc)[WM][2]) const {
;     ...
;           if (ropemode != 0) {
;             const int pc = (ropemode == 1) ? (cc ^ 1) : (cc ^ 2);
;             const float4 p0 = *(const float4*)(T + lr * LD + pc * 8), p1 = *(const float4*)(T + lr * LD + pc * 8 + 4);
;             const float4 c0 = *(const float4*)(bias + nt * 128 + pc * 8), c1 = *(const float4*)(bias + nt * 128 + pc * 8 + 4);
;             const float pr[8] = {p0.x + c0.x, p0.y + c0.y, p0.z + c0.z, p0.w + c0.w, p1.x + c1.x, p1.y + c1.y, p1.z + c1.z, p1.w + c1.w};
;             const int tok = t - NCTX;
;             const int q = (ropemode == 1) ? (cc & 3) : ((cc & 7) >> 1);
;             const int pos = (q < 2) ? (tok >> 6) : (tok & 63);
;             const float2* tab = (ropemode == 1) ? (T32 + pos * 8) : (T64 + pos * 16 + (cc & 1) * 8);
;             const float sgn = (q & 1) ? 1.f : -1.f;
; #pragma unroll
;             for (int k = 0; k < 8; ++k) { const float2 cs = tab[k]; v[k] = v[k] * cs.x + sgn * pr[k] * cs.y; }
.Lrp_l_1_5:
	global_load_dwordx4 v[228:231], v[120:121], off
	global_load_dwordx4 v[232:235], v[120:121], off offset:16
	global_load_dwordx4 v[236:239], v[120:121], off offset:32
	global_load_dwordx4 v[240:243], v[120:121], off offset:48
	s_waitcnt vmcnt(4) lgkmcnt(1)
	v_add_f32_e32 v16, v20, v213
	v_add_f32_e32 v17, v21, v218
	v_add_f32_e32 v20, v22, v219
	v_add_f32_e32 v21, v23, v245
	s_waitcnt lgkmcnt(0)
	v_add_f32_e32 v22, v12, v250
	v_add_f32_e32 v23, v13, v251
	v_add_f32_e32 v25, v14, v126
	v_add_f32_e32 v34, v15, v127
	v_mov_b32_e32 v8, v112
	v_mov_b32_e32 v9, v113
	v_mov_b32_e32 v10, v114
	v_mov_b32_e32 v11, v115
	v_mov_b32_e32 v15, v5
	v_cndmask_b32_e64 v14, v16, -v16, s[0:1]
	v_cndmask_b32_e64 v20, v20, -v20, s[0:1]
	v_cndmask_b32_e64 v22, v22, -v22, s[0:1]
	s_waitcnt vmcnt(4) lgkmcnt(0)
	v_mov_b32_e32 v12, v9
	v_cndmask_b32_e64 v9, v17, -v17, s[0:1]
	v_mov_b32_e32 v5, v9
	v_mov_b32_e32 v9, v11
	v_mov_b32_e32 v13, v10
	v_pk_mul_f32 v[16:17], v[4:5], v[8:9]
	v_mov_b32_e32 v8, v116
	v_mov_b32_e32 v9, v117
	v_mov_b32_e32 v10, v118
	v_mov_b32_e32 v11, v119
	v_cndmask_b32_e64 v4, v21, -v21, s[0:1]
	v_mov_b32_e32 v21, v7
	v_mov_b32_e32 v7, v4
	s_waitcnt vmcnt(4) lgkmcnt(0)
	v_mov_b32_e32 v18, v9
	v_mov_b32_e32 v9, v11
	v_pk_mul_f32 v[8:9], v[6:7], v[8:9]
	v_mov_b32_e32 v4, v214
	v_mov_b32_e32 v5, v215
	v_mov_b32_e32 v6, v216
	v_mov_b32_e32 v7, v217
	v_mov_b32_e32 v19, v10
	s_waitcnt vmcnt(4) lgkmcnt(0)
	v_mov_b32_e32 v10, v5
	v_cndmask_b32_e64 v5, v23, -v23, s[0:1]
	v_mov_b32_e32 v23, v1
	v_mov_b32_e32 v1, v5
	v_mov_b32_e32 v5, v7
	v_mov_b32_e32 v11, v6
	v_pk_mul_f32 v[0:1], v[0:1], v[4:5]
	v_mov_b32_e32 v4, v246
	v_mov_b32_e32 v5, v247
	v_mov_b32_e32 v6, v248
	v_mov_b32_e32 v7, v249
	v_pk_fma_f32 v[0:1], v[22:23], v[10:11], v[0:1]
	s_waitcnt vmcnt(4) lgkmcnt(0)
	v_mul_f32_e32 v2, v2, v4
	v_cndmask_b32_e64 v4, v25, -v25, s[0:1]
	v_mul_f32_e32 v26, v4, v5
	v_cndmask_b32_e64 v5, v34, -v34, s[0:1]
	v_mov_b32_e32 v4, v3
	v_pk_mul_f32 v[4:5], v[4:5], v[6:7]
	v_pk_fma_f32 v[6:7], v[20:21], v[18:19], v[8:9]
	v_mov_b32_e32 v3, v4
	v_mov_b32_e32 v27, v5
	v_pk_fma_f32 v[4:5], v[14:15], v[12:13], v[16:17]
	v_pk_add_f32 v[2:3], v[2:3], v[26:27]

;   DI void operator()(int mt, int nt, int wm, int wn, int r, int h, f32x16 (&acc)[WM][2]) const {
;     ...
;       for (int j = 0; j < 8; ++j) {
;         const int id = tid + 256 * j;
;         const int lr = id >> 4, cc = id & 15;
;         const int row = mt * (WM * 64) + (lr >> 6) * (WM * 32) + ps * 64 + (lr & 63);
;         const int col0 = nt * 128 + cc * 8;
;         if (col0 < PW) {
;           const int t = row % NTOK;
;           const int ropemode = (t >= NCTX) ? ropemode0 : 0;
;           const float4 a0 = *(const float4*)(T + lr * LD + cc * 8), a1 = *(const float4*)(T + lr * LD + cc * 8 + 4);
;           const float4 b0 = *(const float4*)(bias + col0), b1 = *(const float4*)(bias + col0 + 4);
;           float v[8] = {a0.x + b0.x, a0.y + b0.y, a0.z + b0.z, a0.w + b0.w, a1.x + b1.x, a1.y + b1.y, a1.z + b1.z, a1.w + b1.w};
;           if (ropemode != 0) {
;             const int pc = (ropemode == 1) ? (cc ^ 1) : (cc ^ 2);
;             const float4 p0 = *(const float4*)(T + lr * LD + pc * 8), p1 = *(const float4*)(T + lr * LD + pc * 8 + 4);
;             const float4 c0 = *(const float4*)(bias + nt * 128 + pc * 8), c1 = *(const float4*)(bias + nt * 128 + pc * 8 + 4);
.LBB0_335:
	s_or_b64 exec, exec, s[8:9]
	v_add_u32_e32 v34, s43, v202
	s_and_saveexec_b64 s[8:9], s[6:7]
	s_cbranch_execz .LBB0_344
	v_or_b32_e32 v24, v34, v196
	v_mul_hi_i32 v16, v24, s55
	ds_read_b128 v[4:7], v197
	ds_read_b128 v[12:15], v197 offset:16
	v_lshrrev_b32_e32 v17, 31, v16
	v_ashrrev_i32_e32 v16, 9, v16
	v_add_u32_e32 v16, v16, v17
	v_mul_i32_i24_e32 v16, 0x900, v16
	v_sub_u32_e32 v25, v24, v16
	s_xor_b64 s[26:27], s[46:47], -1
	v_cmp_lt_i32_e32 vcc, s62, v25
	s_and_b64 s[28:29], vcc, s[26:27]
	s_waitcnt lgkmcnt(0)
	v_pk_add_f32 v[4:5], v[4:5], v[220:221]
	v_pk_add_f32 v[6:7], v[6:7], v[222:223]
	v_pk_add_f32 v[0:1], v[12:13], v[224:225]
	v_pk_add_f32 v[2:3], v[14:15], v[226:227]
	s_and_saveexec_b64 s[26:27], s[28:29]
	s_cbranch_execz .LBB0_342
	s_lshl_b64 s[28:29], s[24:25], 2
	s_add_u32 s28, s14, s28
	v_lshlrev_b32_e32 v12, 2, v132
	s_addc_u32 s29, s15, s29
	v_add_u32_e32 v12, v108, v12
	ds_read_b128 v[20:23], v12
	ds_read_b128 v[12:15], v12 offset:16
	v_add_u32_e32 v26, 0xffffff00, v25
	v_lshrrev_b32_e32 v26, 6, v26
	v_and_b32_e32 v25, 63, v25
	v_cndmask_b32_e64 v25, v25, v26, s[4:5]
	s_andn2_b64 vcc, exec, s[44:45]
	s_mov_b64 s[28:29], -1
	s_cbranch_vccnz .LBB0_339
	v_lshlrev_b32_e32 v160, 6, v25
	v_lshl_add_u64 v[26:27], s[18:19], 0, v[160:161]
	s_mov_b64 s[28:29], 0

;   DI void operator()(int mt, int nt, int wm, int wn, int r, int h, f32x16 (&acc)[WM][2]) const {
;     ...
;         const int lr = id >> 4, cc = id & 15;
;         const int row = mt * (WM * 64) + (lr >> 6) * (WM * 32) + ps * 64 + (lr & 63);
;         const int col0 = nt * 128 + cc * 8;
;         if (col0 < PW) {
;           const int t = row % NTOK;
;           const int ropemode = (t >= NCTX) ? ropemode0 : 0;
;           const float4 a0 = *(const float4*)(T + lr * LD + cc * 8), a1 = *(const float4*)(T + lr * LD + cc * 8 + 4);
;           const float4 b0 = *(const float4*)(bias + col0), b1 = *(const float4*)(bias + col0 + 4);
;           float v[8] = {a0.x + b0.x, a0.y + b0.y, a0.z + b0.z, a0.w + b0.w, a1.x + b1.x, a1.y + b1.y, a1.z + b1.z, a1.w + b1.w};
;           if (ropemode != 0) {
;             const int pc = (ropemode == 1) ? (cc ^ 1) : (cc ^ 2);
;             const float4 p0 = *(const float4*)(T + lr * LD + pc * 8), p1 = *(const float4*)(T + lr * LD + pc * 8 + 4);
;             const float4 c0 = *(const float4*)(bias + nt * 128 + pc * 8), c1 = *(const float4*)(bias + nt * 128 + pc * 8 + 4);
;             const float pr[8] = {p0.x + c0.x, p0.y + c0.y, p0.z + c0.z, p0.w + c0.w, p1.x + c1.x, p1.y + c1.y, p1.z + c1.z, p1.w + c1.w};
;             const int tok = t - NCTX;
;             const int q = (ropemode == 1) ? (cc & 3) : ((cc & 7) >> 1);
;             const int pos = (q < 2) ? (tok >> 6) : (tok & 63);
;             const float2* tab = (ropemode == 1) ? (T32 + pos * 8) : (T64 + pos * 16 + (cc & 1) * 8);
.LBB0_341:
	v_add_u32_e32 v122, 0x700, v204
	v_ashrrev_i32_e32 v124, 4, v122
	v_ashrrev_i32_e32 v122, 3, v122
	v_and_b32_e32 v122, 0xffffff80, v122
	v_and_b32_e32 v124, 63, v124
	v_add_u32_e32 v122, s43, v122
	v_or_b32_e32 v122, v122, v124
	v_mul_hi_i32 v124, v122, s55
	v_lshrrev_b32_e32 v160, 31, v124
	v_ashrrev_i32_e32 v124, 9, v124
	v_add_u32_e32 v124, v124, v160
	v_mul_i32_i24_e32 v124, 0x900, v124
	v_sub_u32_e32 v122, v122, v124
	v_add_u32_e32 v124, 0xffffff00, v122
	v_lshrrev_b32_e32 v124, 6, v124
	v_and_b32_e32 v122, 63, v122
	v_cndmask_b32_e64 v122, v122, v124, s[4:5]
	s_andn2_b64 vcc, exec, s[44:45]
	s_cbranch_vccnz .Lrp_b_1_6
	v_lshlrev_b32_e32 v160, 6, v122
	v_lshl_add_u64 v[120:121], s[18:19], 0, v[160:161]
	s_branch .Lrp_l_1_6

;   DI void operator()(int mt, int nt, int wm, int wn, int r, int h, f32x16 (&acc)[WM][2]) const {
;     ...
;           if (ropemode != 0) {
;             const int pc = (ropemode == 1) ? (cc ^ 1) : (cc ^ 2);
;             const float4 p0 = *(const float4*)(T + lr * LD + pc * 8), p1 = *(const float4*)(T + lr * LD + pc * 8 + 4);
;             const float4 c0 = *(const float4*)(bias + nt * 128 + pc * 8), c1 = *(const float4*)(bias + nt * 128 + pc * 8 + 4);
;             const float pr[8] = {p0.x + c0.x, p0.y + c0.y, p0.z + c0.z, p0.w + c0.w, p1.x + c1.x, p1.y + c1.y, p1.z + c1.z, p1.w + c1.w};
;             const int tok = t - NCTX;
;             const int q = (ropemode == 1) ? (cc & 3) : ((cc & 7) >> 1);
;             const int pos = (q < 2) ? (tok >> 6) : (tok & 63);
;             const float2* tab = (ropemode == 1) ? (T32 + pos * 8) : (T64 + pos * 16 + (cc & 1) * 8);
;             const float sgn = (q & 1) ? 1.f : -1.f;
; #pragma unroll
;             for (int k = 0; k < 8; ++k) { const float2 cs = tab[k]; v[k] = v[k] * cs.x + sgn * pr[k] * cs.y; }
.Lrp_l_1_6:
	global_load_dwordx4 v[112:115], v[120:121], off
	global_load_dwordx4 v[116:119], v[120:121], off offset:16
	global_load_dwordx4 v[214:217], v[120:121], off offset:32
	global_load_dwordx4 v[246:249], v[120:121], off offset:48
	s_waitcnt vmcnt(4) lgkmcnt(1)
	v_add_f32_e32 v16, v20, v213
	v_add_f32_e32 v17, v21, v218
	v_add_f32_e32 v20, v22, v219
	v_add_f32_e32 v21, v23, v245
	s_waitcnt lgkmcnt(0)
	v_add_f32_e32 v22, v12, v250
	v_add_f32_e32 v23, v13, v251
	v_add_f32_e32 v25, v14, v126
	v_add_f32_e32 v35, v15, v127
	v_mov_b32_e32 v8, v228
	v_mov_b32_e32 v9, v229
	v_mov_b32_e32 v10, v230
	v_mov_b32_e32 v11, v231
	v_mov_b32_e32 v15, v5
	v_cndmask_b32_e64 v14, v16, -v16, s[0:1]
	v_cndmask_b32_e64 v20, v20, -v20, s[0:1]
	v_cndmask_b32_e64 v22, v22, -v22, s[0:1]
	s_waitcnt vmcnt(4) lgkmcnt(0)
	v_mov_b32_e32 v12, v9
	v_cndmask_b32_e64 v9, v17, -v17, s[0:1]
	v_mov_b32_e32 v5, v9
	v_mov_b32_e32 v9, v11
	v_mov_b32_e32 v13, v10
	v_pk_mul_f32 v[16:17], v[4:5], v[8:9]
	v_mov_b32_e32 v8, v232
	v_mov_b32_e32 v9, v233
	v_mov_b32_e32 v10, v234
	v_mov_b32_e32 v11, v235
	v_cndmask_b32_e64 v4, v21, -v21, s[0:1]
	v_mov_b32_e32 v21, v7
	v_mov_b32_e32 v7, v4
	s_waitcnt vmcnt(4) lgkmcnt(0)
	v_mov_b32_e32 v18, v9
	v_mov_b32_e32 v9, v11
	v_pk_mul_f32 v[8:9], v[6:7], v[8:9]
	v_mov_b32_e32 v4, v236
	v_mov_b32_e32 v5, v237
	v_mov_b32_e32 v6, v238
	v_mov_b32_e32 v7, v239
	v_mov_b32_e32 v19, v10
	s_waitcnt vmcnt(4) lgkmcnt(0)
	v_mov_b32_e32 v10, v5
	v_cndmask_b32_e64 v5, v23, -v23, s[0:1]
	v_mov_b32_e32 v23, v1
	v_mov_b32_e32 v1, v5
	v_mov_b32_e32 v5, v7
	v_mov_b32_e32 v11, v6
	v_pk_mul_f32 v[0:1], v[0:1], v[4:5]
	v_mov_b32_e32 v4, v240
	v_mov_b32_e32 v5, v241
	v_mov_b32_e32 v6, v242
	v_mov_b32_e32 v7, v243
	v_pk_fma_f32 v[0:1], v[22:23], v[10:11], v[0:1]
	s_waitcnt vmcnt(4) lgkmcnt(0)
	v_mul_f32_e32 v2, v2, v4
	v_cndmask_b32_e64 v4, v25, -v25, s[0:1]
	v_mul_f32_e32 v26, v4, v5
	v_cndmask_b32_e64 v5, v35, -v35, s[0:1]
	v_mov_b32_e32 v4, v3
	v_pk_mul_f32 v[4:5], v[4:5], v[6:7]
	v_pk_fma_f32 v[6:7], v[20:21], v[18:19], v[8:9]
	v_mov_b32_e32 v3, v4
	v_mov_b32_e32 v27, v5
	v_pk_fma_f32 v[4:5], v[14:15], v[12:13], v[16:17]
	v_pk_add_f32 v[2:3], v[2:3], v[26:27]

;   DI void operator()(int mt, int nt, int wm, int wn, int r, int h, f32x16 (&acc)[WM][2]) const {
;     ...
;       for (int j = 0; j < 8; ++j) {
;         const int id = tid + 256 * j;
;         const int lr = id >> 4, cc = id & 15;
;         const int row = mt * (WM * 64) + (lr >> 6) * (WM * 32) + ps * 64 + (lr & 63);
;         const int col0 = nt * 128 + cc * 8;
;         if (col0 < PW) {
;           const int t = row % NTOK;
;           const int ropemode = (t >= NCTX) ? ropemode0 : 0;
;           const float4 a0 = *(const float4*)(T + lr * LD + cc * 8), a1 = *(const float4*)(T + lr * LD + cc * 8 + 4);
;           const float4 b0 = *(const float4*)(bias + col0), b1 = *(const float4*)(bias + col0 + 4);
;           float v[8] = {a0.x + b0.x, a0.y + b0.y, a0.z + b0.z, a0.w + b0.w, a1.x + b1.x, a1.y + b1.y, a1.z + b1.z, a1.w + b1.w};
;           if (ropemode != 0) {
;             const int pc = (ropemode == 1) ? (cc ^ 1) : (cc ^ 2);
;             const float4 p0 = *(const float4*)(T + lr * LD + pc * 8), p1 = *(const float4*)(T + lr * LD + pc * 8 + 4);
;             const float4 c0 = *(const float4*)(bias + nt * 128 + pc * 8), c1 = *(const float4*)(bias + nt * 128 + pc * 8 + 4);
.LBB0_344:
	s_or_b64 exec, exec, s[8:9]
	v_add_u32_e32 v35, s43, v203
	s_and_saveexec_b64 s[8:9], s[6:7]
	s_cbranch_execz .LBB0_353
	v_or_b32_e32 v24, v35, v199
	v_mul_hi_i32 v16, v24, s55
	ds_read_b128 v[4:7], v200
	ds_read_b128 v[12:15], v200 offset:16
	v_lshrrev_b32_e32 v17, 31, v16
	v_ashrrev_i32_e32 v16, 9, v16
	v_add_u32_e32 v16, v16, v17
	v_mul_i32_i24_e32 v16, 0x900, v16
	v_sub_u32_e32 v25, v24, v16
	s_xor_b64 s[6:7], s[46:47], -1
	v_cmp_lt_i32_e32 vcc, s62, v25
	s_and_b64 s[26:27], vcc, s[6:7]
	s_waitcnt lgkmcnt(0)
	v_pk_add_f32 v[4:5], v[4:5], v[220:221]
	v_pk_add_f32 v[6:7], v[6:7], v[222:223]
	v_pk_add_f32 v[0:1], v[12:13], v[224:225]
	v_pk_add_f32 v[2:3], v[14:15], v[226:227]
	s_and_saveexec_b64 s[6:7], s[26:27]
	s_cbranch_execz .LBB0_351
	s_lshl_b64 s[24:25], s[24:25], 2
	s_add_u32 s24, s14, s24
	v_lshlrev_b32_e32 v12, 2, v132
	s_addc_u32 s25, s15, s25
	v_add_u32_e32 v12, v109, v12
	ds_read_b128 v[20:23], v12
	ds_read_b128 v[12:15], v12 offset:16
	v_add_u32_e32 v26, 0xffffff00, v25
	v_lshrrev_b32_e32 v26, 6, v26
	v_and_b32_e32 v25, 63, v25
	v_cndmask_b32_e64 v25, v25, v26, s[4:5]
	s_andn2_b64 vcc, exec, s[44:45]
	s_mov_b64 s[4:5], -1
	s_cbranch_vccnz .LBB0_348
	v_lshlrev_b32_e32 v160, 6, v25
	v_lshl_add_u64 v[26:27], s[18:19], 0, v[160:161]
	s_mov_b64 s[4:5], 0

;   DI void operator()(int mt, int nt, int wm, int wn, int r, int h, f32x16 (&acc)[WM][2]) const {
;     ...
;           if (ropemode != 0) {
;             const int pc = (ropemode == 1) ? (cc ^ 1) : (cc ^ 2);
;             const float4 p0 = *(const float4*)(T + lr * LD + pc * 8), p1 = *(const float4*)(T + lr * LD + pc * 8 + 4);
;             const float4 c0 = *(const float4*)(bias + nt * 128 + pc * 8), c1 = *(const float4*)(bias + nt * 128 + pc * 8 + 4);
;             const float pr[8] = {p0.x + c0.x, p0.y + c0.y, p0.z + c0.z, p0.w + c0.w, p1.x + c1.x, p1.y + c1.y, p1.z + c1.z, p1.w + c1.w};
;             const int tok = t - NCTX;
;             const int q = (ropemode == 1) ? (cc & 3) : ((cc & 7) >> 1);
;             const int pos = (q < 2) ? (tok >> 6) : (tok & 63);
;             const float2* tab = (ropemode == 1) ? (T32 + pos * 8) : (T64 + pos * 16 + (cc & 1) * 8);
;             const float sgn = (q & 1) ? 1.f : -1.f;
; #pragma unroll
;             for (int k = 0; k < 8; ++k) { const float2 cs = tab[k]; v[k] = v[k] * cs.x + sgn * pr[k] * cs.y; }
.LBB0_350:
	s_waitcnt vmcnt(0) lgkmcnt(1)
	v_add_f32_e32 v16, v20, v213
	v_add_f32_e32 v17, v21, v218
	v_add_f32_e32 v20, v22, v219
	v_add_f32_e32 v21, v23, v245
	s_waitcnt lgkmcnt(0)
	v_add_f32_e32 v22, v12, v250
	v_add_f32_e32 v23, v13, v251
	v_add_f32_e32 v25, v14, v126
	v_add_f32_e32 v36, v15, v127
	v_mov_b32_e32 v8, v112
	v_mov_b32_e32 v9, v113
	v_mov_b32_e32 v10, v114
	v_mov_b32_e32 v11, v115
	v_mov_b32_e32 v15, v5
	v_cndmask_b32_e64 v14, v16, -v16, s[0:1]
	v_cndmask_b32_e64 v20, v20, -v20, s[0:1]
	v_cndmask_b32_e64 v22, v22, -v22, s[0:1]
	s_waitcnt vmcnt(0) lgkmcnt(0)
	v_mov_b32_e32 v12, v9
	v_cndmask_b32_e64 v9, v17, -v17, s[0:1]
	v_mov_b32_e32 v5, v9
	v_mov_b32_e32 v9, v11
	v_mov_b32_e32 v13, v10
	v_pk_mul_f32 v[16:17], v[4:5], v[8:9]
	v_mov_b32_e32 v8, v116
	v_mov_b32_e32 v9, v117
	v_mov_b32_e32 v10, v118
	v_mov_b32_e32 v11, v119
	v_cndmask_b32_e64 v4, v21, -v21, s[0:1]
	v_mov_b32_e32 v21, v7
	v_mov_b32_e32 v7, v4
	s_waitcnt vmcnt(0) lgkmcnt(0)
	v_mov_b32_e32 v18, v9
	v_mov_b32_e32 v9, v11
	v_pk_mul_f32 v[8:9], v[6:7], v[8:9]
	v_mov_b32_e32 v4, v214
	v_mov_b32_e32 v5, v215
	v_mov_b32_e32 v6, v216
	v_mov_b32_e32 v7, v217
	v_mov_b32_e32 v19, v10
	s_waitcnt vmcnt(0) lgkmcnt(0)
	v_mov_b32_e32 v10, v5
	v_cndmask_b32_e64 v5, v23, -v23, s[0:1]
	v_mov_b32_e32 v23, v1
	v_mov_b32_e32 v1, v5
	v_mov_b32_e32 v5, v7
	v_mov_b32_e32 v11, v6
	v_pk_mul_f32 v[0:1], v[0:1], v[4:5]
	v_mov_b32_e32 v4, v246
	v_mov_b32_e32 v5, v247
	v_mov_b32_e32 v6, v248
	v_mov_b32_e32 v7, v249
	v_pk_fma_f32 v[0:1], v[22:23], v[10:11], v[0:1]
	s_waitcnt vmcnt(0) lgkmcnt(0)
	v_mul_f32_e32 v2, v2, v4
	v_cndmask_b32_e64 v4, v25, -v25, s[0:1]
	v_mul_f32_e32 v26, v4, v5
	v_cndmask_b32_e64 v5, v36, -v36, s[0:1]
	v_mov_b32_e32 v4, v3
	v_pk_mul_f32 v[4:5], v[4:5], v[6:7]
	v_pk_fma_f32 v[6:7], v[20:21], v[18:19], v[8:9]
	v_mov_b32_e32 v3, v4
	v_mov_b32_e32 v27, v5
	v_pk_fma_f32 v[4:5], v[14:15], v[12:13], v[16:17]
	v_pk_add_f32 v[2:3], v[2:3], v[26:27]
